# P1 epilogue tile stores also write-through and the P1 barrier write-back dropped (weight-conversion stores stay write-back: consumed from P3, flushed at the P2 barrier)
# baseline (speedup 1.0000x reference)
; __device__ __forceinline__ float fast_exp(float x) { return __builtin_amdgcn_exp2f(x * LOG2E); }
; __device__ __forceinline__ float silu_f(float x) { return x * __builtin_amdgcn_rcpf(1.f + fast_exp(-x)); }
; __device__ __forceinline__ void st_bf8(bf16* p, const f32x4 a, const f32x4 b) { *(GAS v4u*)p = (v4u){pk2(a.x, a.y), pk2(a.z, a.w), pk2(b.x, b.y), pk2(b.z, b.w)}; }
;     template <int NR> __device__ __forceinline__ void rows(const int (&rowb)[NR], int fr, const float (&rstd)[NR], const f32x4 (&a)[NR][2][2], int pn, int wc, int fq) const {
;     ...
;         for (int i = 0; i < NR; ++i) {
;             const float rr = rstd[i];
; #pragma unroll
;             for (int bj = 0; bj < 2; ++bj) {
;                 f32x4 u = a[i][bj][0] * rr, v = a[i][bj][1] * rr;
;                 const size_t off = (tile_ub(rowb[i], c0b + 32 * bj, DM) + ltb) >> 1;
;                 if (blk == 0) {
; #pragma unroll
;                     for (int j = 0; j < 4; ++j) { u[j] = silu_f(u[j]); v[j] = silu_f(v[j]); }
;                     st_bf8(QH + off, u, v);
;                 } else if (blk == 1) {
; #pragma unroll
;                     for (int j = 0; j < 4; ++j) { const float s0 = __builtin_amdgcn_rcpf(1.f + fast_exp(-u[j])), s1 = __builtin_amdgcn_rcpf(1.f + fast_exp(-v[j])); u[j] = __logf(l[bj][0][j] + (1.f - l[bj][0][j]) * s0); v[j] = __logf(l[bj][1][j] + (1.f - l[bj][1][j]) * s1); }
;                     st_bf8(LOGF + off, u, v);
;                 } else if (blk == 2) {
;                     st_bf8(VH + off, u, v);
;                 } else {
; #pragma unroll
;                     for (int j = 0; j < 4; ++j) { u[j] = silu_f(u[j]); v[j] = silu_f(v[j]); }
;                     st_bf8(GH + off, u, v);
.LBB0_100:
	v_cvt_pk_bf16_f32 v13, v24, v25
	global_store_dwordx4 v[26:27], v[10:13], off sc1

; __device__ __forceinline__ float fast_exp(float x) { return __builtin_amdgcn_exp2f(x * LOG2E); }
; __device__ __forceinline__ float silu_f(float x) { return x * __builtin_amdgcn_rcpf(1.f + fast_exp(-x)); }
;     template <int NR> __device__ __forceinline__ void rows(const int (&rowb)[NR], int fr, const float (&rstd)[NR], const f32x4 (&a)[NR][2][2], int pn, int wc, int fq) const {
;     ...
;         for (int i = 0; i < NR; ++i) {
;             const float rr = rstd[i];
; #pragma unroll
;             for (int bj = 0; bj < 2; ++bj) {
;                 f32x4 u = a[i][bj][0] * rr, v = a[i][bj][1] * rr;
;                 const size_t off = (tile_ub(rowb[i], c0b + 32 * bj, DM) + ltb) >> 1;
;                 if (blk == 0) {
; #pragma unroll
;                     for (int j = 0; j < 4; ++j) { u[j] = silu_f(u[j]); v[j] = silu_f(v[j]); }
;                     st_bf8(QH + off, u, v);
;                 } else if (blk == 1) {
; #pragma unroll
;                     for (int j = 0; j < 4; ++j) { const float s0 = __builtin_amdgcn_rcpf(1.f + fast_exp(-u[j])), s1 = __builtin_amdgcn_rcpf(1.f + fast_exp(-v[j])); u[j] = __logf(l[bj][0][j] + (1.f - l[bj][0][j]) * s0); v[j] = __logf(l[bj][1][j] + (1.f - l[bj][1][j]) * s1); }
;                     st_bf8(LOGF + off, u, v);
;                 } else if (blk == 2) {
;                     st_bf8(VH + off, u, v);
;                 } else {
; #pragma unroll
;                     for (int j = 0; j < 4; ++j) { u[j] = silu_f(u[j]); v[j] = silu_f(v[j]); }
;                     st_bf8(GH + off, u, v);
; template <class RowEpi, int MTL>
; __device__ __forceinline__ void small_gemm_t(Frame& F, const bf16* A  , const bf16* Bt, int N, int K, const RowEpi& R, int i_lo, int i_hi) {
;     ...
;         if (w < MTL) {
;             f32x4 s[2][2];
; #pragma unroll
;             for (int bj = 0; bj < 2; ++bj)
; #pragma unroll
;                 for (int n = 0; n < 2; ++n) { f32x4 t = (f32x4){0.f, 0.f, 0.f, 0.f};
; #pragma unroll
;                     for (int ww = 0; ww < 8; ++ww) t += part[(ww * (4 * MTL) + w * 4 + bj * 2 + n) * 64 + lane];
;                     s[bj][n] = t; }
;             const int row1[1] = {MP + rb * 16 * MTL + 16 * w}; const f32x4 a1[1][2][2] = {{{s[0][0], s[0][1]}, {s[1][0], s[1][1]}}};
;             const float rr1[1] = {rsp ? rsqrtf(rsv * (1.f / DM) + EPS) : 1.f};
;             R.template rows<1>(row1, fr, rr1, a1, pn, wc, fq);
.LBB0_121:
	s_waitcnt lgkmcnt(11)
	v_pk_add_f32 v[60:61], v[60:61], 0 op_sel_hi:[1,0]
	v_pk_add_f32 v[58:59], v[58:59], 0 op_sel_hi:[1,0]
	s_waitcnt lgkmcnt(10)
	v_pk_add_f32 v[16:17], v[16:17], 0 op_sel_hi:[1,0]
	v_pk_add_f32 v[14:15], v[14:15], 0 op_sel_hi:[1,0]
	s_waitcnt lgkmcnt(9)
	v_pk_add_f32 v[52:53], v[60:61], v[52:53]
	v_pk_add_f32 v[50:51], v[58:59], v[50:51]
	s_waitcnt lgkmcnt(8)
	v_pk_add_f32 v[12:13], v[16:17], v[12:13]
	v_pk_add_f32 v[10:11], v[14:15], v[10:11]
	s_waitcnt lgkmcnt(7)
	v_pk_add_f32 v[52:53], v[52:53], v[72:73]
	v_pk_add_f32 v[50:51], v[50:51], v[70:71]
	s_waitcnt lgkmcnt(6)
	v_pk_add_f32 v[12:13], v[12:13], v[64:65]
	v_pk_add_f32 v[10:11], v[10:11], v[62:63]
	s_waitcnt lgkmcnt(5)
	v_pk_add_f32 v[52:53], v[52:53], v[68:69]
	v_pk_add_f32 v[50:51], v[50:51], v[66:67]
	s_waitcnt lgkmcnt(4)
	v_pk_add_f32 v[12:13], v[12:13], v[56:57]
	v_pk_add_f32 v[10:11], v[10:11], v[54:55]
	v_pk_add_f32 v[32:33], v[52:53], v[32:33]
	v_pk_add_f32 v[30:31], v[50:51], v[30:31]
	s_waitcnt lgkmcnt(3)
	v_pk_add_f32 v[12:13], v[12:13], v[48:49]
	v_pk_add_f32 v[10:11], v[10:11], v[46:47]
	v_pk_add_f32 v[24:25], v[32:33], v[24:25]
	v_pk_add_f32 v[22:23], v[30:31], v[22:23]
	s_waitcnt lgkmcnt(2)
	v_pk_add_f32 v[12:13], v[12:13], v[44:45]
	v_pk_add_f32 v[10:11], v[10:11], v[42:43]
	v_pk_add_f32 v[24:25], v[24:25], v[28:29]
	v_pk_add_f32 v[22:23], v[22:23], v[26:27]
	s_waitcnt lgkmcnt(1)
	v_pk_add_f32 v[12:13], v[12:13], v[40:41]
	v_pk_add_f32 v[10:11], v[10:11], v[38:39]
	v_mov_b32_e32 v87, v86
	v_pk_add_f32 v[20:21], v[24:25], v[20:21]
	v_pk_add_f32 v[18:19], v[22:23], v[18:19]
	s_waitcnt lgkmcnt(0)
	v_pk_add_f32 v[12:13], v[12:13], v[36:37]
	v_pk_add_f32 v[10:11], v[10:11], v[34:35]
	v_mov_b32_e32 v14, v86
	v_mov_b32_e32 v15, v86
	s_bitset1_b32 s14, 10
	v_cvt_pk_bf16_f32 v85, v100, v101
	v_pk_mul_f32 v[16:17], v[14:15], v[20:21]
	v_pk_mul_f32 v[18:19], v[86:87], v[18:19]
	v_pk_mul_f32 v[14:15], v[14:15], v[12:13]
	v_pk_mul_f32 v[22:23], v[86:87], v[10:11]
	v_lshl_add_u64 v[20:21], v[88:89], 0, s[14:15]
	s_andn2_b64 vcc, exec, s[6:7]
	s_mov_b64 s[6:7], -1
	global_store_dwordx4 v[102:103], v[82:85], off sc1
	s_cbranch_vccnz .LBB0_131
	s_andn2_b64 vcc, exec, s[24:25]
	s_cbranch_vccnz .LBB0_128
	s_andn2_b64 vcc, exec, s[4:5]
	s_mov_b64 s[4:5], -1
	s_cbranch_vccnz .LBB0_125
	v_mul_f32_e32 v11, 0xbfb8aa3b, v22
	v_mul_f32_e32 v12, 0xbfb8aa3b, v19
	v_exp_f32_e32 v11, v11
	v_exp_f32_e32 v13, v12
	v_mul_f32_e32 v12, 0xbfb8aa3b, v23
	v_exp_f32_e32 v24, v12
	v_add_f32_e32 v11, 1.0, v11
	v_mul_f32_e32 v25, 0xbfb8aa3b, v14
	v_mul_f32_e32 v10, 0xbfb8aa3b, v18
	v_rcp_f32_e32 v12, v11
	v_add_f32_e32 v11, 1.0, v13
	v_add_f32_e32 v13, 1.0, v24
	v_mul_f32_e32 v24, 0xbfb8aa3b, v16
	v_exp_f32_e32 v25, v25
	v_mul_f32_e32 v26, 0xbfb8aa3b, v17
	v_exp_f32_e32 v10, v10
	v_exp_f32_e32 v24, v24
	v_exp_f32_e32 v27, v26
	v_mul_f32_e32 v26, 0xbfb8aa3b, v15
	v_exp_f32_e32 v28, v26
	v_add_f32_e32 v25, 1.0, v25
	v_add_f32_e32 v10, 1.0, v10
	v_add_f32_e32 v24, 1.0, v24
	v_rcp_f32_e32 v26, v25
	v_add_f32_e32 v25, 1.0, v27
	v_rcp_f32_e32 v10, v10
	v_rcp_f32_e32 v11, v11
	v_rcp_f32_e32 v13, v13
	v_rcp_f32_e32 v24, v24
	v_rcp_f32_e32 v25, v25
	v_add_f32_e32 v27, 1.0, v28
	v_rcp_f32_e32 v27, v27
	v_pk_mul_f32 v[10:11], v[18:19], v[10:11]
	v_pk_mul_f32 v[12:13], v[22:23], v[12:13]
	v_pk_mul_f32 v[28:29], v[16:17], v[24:25]
	v_pk_mul_f32 v[24:25], v[14:15], v[26:27]
	v_lshl_add_u64 v[26:27], s[62:63], 0, v[20:21]
	v_cvt_pk_bf16_f32 v10, v10, v11
	v_cvt_pk_bf16_f32 v11, v28, v29
	v_cvt_pk_bf16_f32 v12, v12, v13
	s_mov_b64 s[4:5], 0

; __device__ __forceinline__ float fast_exp(float x) { return __builtin_amdgcn_exp2f(x * LOG2E); }
; __device__ __forceinline__ float silu_f(float x) { return x * __builtin_amdgcn_rcpf(1.f + fast_exp(-x)); }
; __device__ __forceinline__ void st_bf8(bf16* p, const f32x4 a, const f32x4 b) { *(GAS v4u*)p = (v4u){pk2(a.x, a.y), pk2(a.z, a.w), pk2(b.x, b.y), pk2(b.z, b.w)}; }
;     template <int NR> __device__ __forceinline__ void rows(const int (&rowb)[NR], int fr, const float (&rstd)[NR], const f32x4 (&a)[NR][2][2], int pn, int wc, int fq) const {
;     ...
;         for (int i = 0; i < NR; ++i) {
;             const float rr = rstd[i];
; #pragma unroll
;             for (int bj = 0; bj < 2; ++bj) {
;                 f32x4 u = a[i][bj][0] * rr, v = a[i][bj][1] * rr;
;                 const size_t off = (tile_ub(rowb[i], c0b + 32 * bj, DM) + ltb) >> 1;
;                 if (blk == 0) {
; #pragma unroll
;                     for (int j = 0; j < 4; ++j) { u[j] = silu_f(u[j]); v[j] = silu_f(v[j]); }
;                     st_bf8(QH + off, u, v);
;                 } else if (blk == 1) {
; #pragma unroll
;                     for (int j = 0; j < 4; ++j) { const float s0 = __builtin_amdgcn_rcpf(1.f + fast_exp(-u[j])), s1 = __builtin_amdgcn_rcpf(1.f + fast_exp(-v[j])); u[j] = __logf(l[bj][0][j] + (1.f - l[bj][0][j]) * s0); v[j] = __logf(l[bj][1][j] + (1.f - l[bj][1][j]) * s1); }
;                     st_bf8(LOGF + off, u, v);
;                 } else if (blk == 2) {
;                     st_bf8(VH + off, u, v);
;                 } else {
; #pragma unroll
;                     for (int j = 0; j < 4; ++j) { u[j] = silu_f(u[j]); v[j] = silu_f(v[j]); }
;                     st_bf8(GH + off, u, v);
;                 }
;             }
.LBB0_290:
	s_nop 0
	v_cvt_pk_bf16_f32 v141, v160, v161
	v_mov_b32_e32 v154, v152
	v_mov_b32_e32 v155, v152
	global_store_dwordx4 v[162:163], v[138:141], off sc1
	v_pk_mul_f32 v[144:145], v[134:135], v[154:155]
	s_mov_b64 s[4:5], -1
	v_mov_b32_e32 v140, v152
	v_mov_b32_e32 v141, v152
	v_pk_mul_f32 v[138:139], v[136:137], v[140:141]
	v_pk_mul_f32 v[134:135], v[132:133], v[140:141]
	v_pk_mul_f32 v[140:141], v[130:131], v[154:155]
	v_cndmask_b32_e64 v130, 0, 1, s[86:87]
	v_mov_b32_e32 v137, s13
	v_cmp_ne_u32_e64 s[12:13], 1, v130
	v_cndmask_b32_e64 v130, 0, 1, s[14:15]
	v_or_b32_e32 v136, 0x400, v142
	s_andn2_b64 vcc, exec, s[86:87]
	v_cmp_ne_u32_e64 s[10:11], 1, v130
	s_cbranch_vccnz .LBB0_300
	s_and_b64 vcc, exec, s[10:11]
	s_cbranch_vccnz .LBB0_297
	s_andn2_b64 vcc, exec, s[82:83]
	s_cbranch_vccnz .LBB0_294
	v_mul_f32_e32 v131, 0xbfb8aa3b, v140
	v_mul_f32_e32 v132, 0xbfb8aa3b, v145
	v_exp_f32_e32 v131, v131
	v_exp_f32_e32 v133, v132
	v_mul_f32_e32 v132, 0xbfb8aa3b, v141
	v_exp_f32_e32 v142, v132
	v_add_f32_e32 v131, 1.0, v131
	v_mul_f32_e32 v143, 0xbfb8aa3b, v134
	v_mul_f32_e32 v130, 0xbfb8aa3b, v144
	v_rcp_f32_e32 v132, v131
	v_add_f32_e32 v131, 1.0, v133
	v_add_f32_e32 v133, 1.0, v142
	v_mul_f32_e32 v142, 0xbfb8aa3b, v138
	v_exp_f32_e32 v143, v143
	v_mul_f32_e32 v152, 0xbfb8aa3b, v139
	v_exp_f32_e32 v130, v130
	v_exp_f32_e32 v142, v142
	v_exp_f32_e32 v152, v152
	v_mul_f32_e32 v154, 0xbfb8aa3b, v135
	v_exp_f32_e32 v155, v154
	v_add_f32_e32 v143, 1.0, v143
	v_add_f32_e32 v130, 1.0, v130
	v_add_f32_e32 v142, 1.0, v142
	v_rcp_f32_e32 v154, v143
	v_add_f32_e32 v143, 1.0, v152
	v_rcp_f32_e32 v130, v130
	v_rcp_f32_e32 v131, v131
	v_rcp_f32_e32 v133, v133
	v_rcp_f32_e32 v142, v142
	v_rcp_f32_e32 v143, v143
	v_add_f32_e32 v152, 1.0, v155
	v_rcp_f32_e32 v155, v152
	v_pk_mul_f32 v[130:131], v[144:145], v[130:131]
	v_pk_mul_f32 v[132:133], v[140:141], v[132:133]
	v_pk_mul_f32 v[156:157], v[138:139], v[142:143]
	v_pk_mul_f32 v[142:143], v[134:135], v[154:155]
	v_lshl_add_u64 v[154:155], s[62:63], 0, v[136:137]
	v_cvt_pk_bf16_f32 v130, v130, v131
	v_cvt_pk_bf16_f32 v131, v156, v157
	v_cvt_pk_bf16_f32 v132, v132, v133
	s_mov_b64 s[4:5], 0

; __device__ __forceinline__ float fast_exp(float x) { return __builtin_amdgcn_exp2f(x * LOG2E); }
; __device__ __forceinline__ float silu_f(float x) { return x * __builtin_amdgcn_rcpf(1.f + fast_exp(-x)); }
; __device__ __forceinline__ void st_bf8(bf16* p, const f32x4 a, const f32x4 b) { *(GAS v4u*)p = (v4u){pk2(a.x, a.y), pk2(a.z, a.w), pk2(b.x, b.y), pk2(b.z, b.w)}; }
;     template <int NR> __device__ __forceinline__ void rows(const int (&rowb)[NR], int fr, const float (&rstd)[NR], const f32x4 (&a)[NR][2][2], int pn, int wc, int fq) const {
;     ...
;         for (int i = 0; i < NR; ++i) {
;             const float rr = rstd[i];
; #pragma unroll
;             for (int bj = 0; bj < 2; ++bj) {
;                 f32x4 u = a[i][bj][0] * rr, v = a[i][bj][1] * rr;
;                 const size_t off = (tile_ub(rowb[i], c0b + 32 * bj, DM) + ltb) >> 1;
;                 if (blk == 0) {
; #pragma unroll
;                     for (int j = 0; j < 4; ++j) { u[j] = silu_f(u[j]); v[j] = silu_f(v[j]); }
;                     st_bf8(QH + off, u, v);
;                 } else if (blk == 1) {
; #pragma unroll
;                     for (int j = 0; j < 4; ++j) { const float s0 = __builtin_amdgcn_rcpf(1.f + fast_exp(-u[j])), s1 = __builtin_amdgcn_rcpf(1.f + fast_exp(-v[j])); u[j] = __logf(l[bj][0][j] + (1.f - l[bj][0][j]) * s0); v[j] = __logf(l[bj][1][j] + (1.f - l[bj][1][j]) * s1); }
;                     st_bf8(LOGF + off, u, v);
;                 } else if (blk == 2) {
;                     st_bf8(VH + off, u, v);
;                 } else {
; #pragma unroll
;                     for (int j = 0; j < 4; ++j) { u[j] = silu_f(u[j]); v[j] = silu_f(v[j]); }
;                     st_bf8(GH + off, u, v);
;                 }
;             }
.LBB0_302:
	s_add_i32 s4, s7, s48
	s_ashr_i32 s0, s4, 8
	s_ashr_i32 s1, s0, 31
	v_cvt_pk_bf16_f32 v133, v142, v143
	s_lshl_b64 s[86:87], s[0:1], 19
	s_lshl_b32 s0, s4, 7
	global_store_dwordx4 v[154:155], v[130:133], off sc1
	s_and_b32 s1, s0, 0x4000
	s_and_b32 s0, s0, 0x2800
	v_mov_b32_e32 v132, v153
	v_pk_mul_f32 v[130:131], v[128:129], v[132:133] op_sel_hi:[1,0]
	v_pk_mul_f32 v[134:135], v[126:127], v[132:133] op_sel_hi:[1,0]
	v_pk_mul_f32 v[128:129], v[124:125], v[132:133] op_sel_hi:[1,0]
	v_pk_mul_f32 v[132:133], v[122:123], v[132:133] op_sel_hi:[1,0]
	s_or_b32 s1, s86, s1
	v_or_b32_e32 v122, s0, v170
	v_or_b32_e32 v126, s1, v122
	v_mov_b32_e32 v127, s87
	s_and_b64 vcc, exec, s[12:13]
	s_mov_b64 s[4:5], -1
	s_cbranch_vccnz .LBB0_312
	s_and_b64 vcc, exec, s[10:11]
	s_cbranch_vccnz .LBB0_309
	s_andn2_b64 vcc, exec, s[82:83]
	s_cbranch_vccnz .LBB0_306
	v_mul_f32_e32 v123, 0xbfb8aa3b, v132
	v_mul_f32_e32 v124, 0xbfb8aa3b, v135
	v_exp_f32_e32 v123, v123
	v_exp_f32_e32 v125, v124
	v_mul_f32_e32 v124, 0xbfb8aa3b, v133
	v_exp_f32_e32 v136, v124
	v_add_f32_e32 v123, 1.0, v123
	v_mul_f32_e32 v137, 0xbfb8aa3b, v128
	v_mul_f32_e32 v122, 0xbfb8aa3b, v134
	v_rcp_f32_e32 v124, v123
	v_add_f32_e32 v123, 1.0, v125
	v_add_f32_e32 v125, 1.0, v136
	v_mul_f32_e32 v136, 0xbfb8aa3b, v130
	v_exp_f32_e32 v137, v137
	v_mul_f32_e32 v138, 0xbfb8aa3b, v131
	v_exp_f32_e32 v122, v122
	v_exp_f32_e32 v136, v136
	v_exp_f32_e32 v139, v138
	v_mul_f32_e32 v138, 0xbfb8aa3b, v129
	v_exp_f32_e32 v140, v138
	v_add_f32_e32 v137, 1.0, v137
	v_add_f32_e32 v122, 1.0, v122
	v_add_f32_e32 v136, 1.0, v136
	v_rcp_f32_e32 v138, v137
	v_add_f32_e32 v137, 1.0, v139
	v_rcp_f32_e32 v122, v122
	v_rcp_f32_e32 v123, v123
	v_rcp_f32_e32 v125, v125
	v_rcp_f32_e32 v136, v136
	v_rcp_f32_e32 v137, v137
	v_add_f32_e32 v139, 1.0, v140
	v_rcp_f32_e32 v139, v139
	v_pk_mul_f32 v[122:123], v[134:135], v[122:123]
	v_pk_mul_f32 v[124:125], v[132:133], v[124:125]
	v_pk_mul_f32 v[140:141], v[130:131], v[136:137]
	v_pk_mul_f32 v[136:137], v[128:129], v[138:139]
	v_lshl_add_u64 v[138:139], s[62:63], 0, v[126:127]
	v_cvt_pk_bf16_f32 v122, v122, v123
	v_cvt_pk_bf16_f32 v123, v140, v141
	v_cvt_pk_bf16_f32 v124, v124, v125
	s_mov_b64 s[4:5], 0

; __device__ __forceinline__ float fast_exp(float x) { return __builtin_amdgcn_exp2f(x * LOG2E); }
; __device__ __forceinline__ float silu_f(float x) { return x * __builtin_amdgcn_rcpf(1.f + fast_exp(-x)); }
; __device__ __forceinline__ void st_bf8(bf16* p, const f32x4 a, const f32x4 b) { *(GAS v4u*)p = (v4u){pk2(a.x, a.y), pk2(a.z, a.w), pk2(b.x, b.y), pk2(b.z, b.w)}; }
;     template <int NR> __device__ __forceinline__ void rows(const int (&rowb)[NR], int fr, const float (&rstd)[NR], const f32x4 (&a)[NR][2][2], int pn, int wc, int fq) const {
;     ...
;         for (int i = 0; i < NR; ++i) {
;             const float rr = rstd[i];
; #pragma unroll
;             for (int bj = 0; bj < 2; ++bj) {
;                 f32x4 u = a[i][bj][0] * rr, v = a[i][bj][1] * rr;
;                 const size_t off = (tile_ub(rowb[i], c0b + 32 * bj, DM) + ltb) >> 1;
;                 if (blk == 0) {
; #pragma unroll
;                     for (int j = 0; j < 4; ++j) { u[j] = silu_f(u[j]); v[j] = silu_f(v[j]); }
;                     st_bf8(QH + off, u, v);
;                 } else if (blk == 1) {
; #pragma unroll
;                     for (int j = 0; j < 4; ++j) { const float s0 = __builtin_amdgcn_rcpf(1.f + fast_exp(-u[j])), s1 = __builtin_amdgcn_rcpf(1.f + fast_exp(-v[j])); u[j] = __logf(l[bj][0][j] + (1.f - l[bj][0][j]) * s0); v[j] = __logf(l[bj][1][j] + (1.f - l[bj][1][j]) * s1); }
;                     st_bf8(LOGF + off, u, v);
;                 } else if (blk == 2) {
;                     st_bf8(VH + off, u, v);
;                 } else {
; #pragma unroll
;                     for (int j = 0; j < 4; ++j) { u[j] = silu_f(u[j]); v[j] = silu_f(v[j]); }
;                     st_bf8(GH + off, u, v);
;                 }
;             }
.LBB0_314:
	s_nop 0
	v_cvt_pk_bf16_f32 v125, v136, v137
	v_mov_b32_e32 v152, v153
	global_store_dwordx4 v[138:139], v[122:125], off sc1
	v_pk_mul_f32 v[128:129], v[118:119], v[152:153]
	s_and_b64 vcc, exec, s[12:13]
	v_mov_b32_e32 v124, v153
	v_mov_b32_e32 v125, v153
	v_pk_mul_f32 v[122:123], v[120:121], v[124:125]
	v_pk_mul_f32 v[118:119], v[116:117], v[124:125]
	v_pk_mul_f32 v[124:125], v[114:115], v[152:153]
	v_or_b32_e32 v120, 0x400, v126
	v_mov_b32_e32 v121, s87
	s_mov_b64 s[4:5], -1
	s_cbranch_vccnz .LBB0_324
	s_and_b64 vcc, exec, s[10:11]
	s_cbranch_vccnz .LBB0_321
	s_andn2_b64 vcc, exec, s[82:83]
	s_cbranch_vccnz .LBB0_318
	v_mul_f32_e32 v115, 0xbfb8aa3b, v124
	v_mul_f32_e32 v116, 0xbfb8aa3b, v129
	v_exp_f32_e32 v115, v115
	v_exp_f32_e32 v117, v116
	v_mul_f32_e32 v116, 0xbfb8aa3b, v125
	v_exp_f32_e32 v126, v116
	v_add_f32_e32 v115, 1.0, v115
	v_mul_f32_e32 v127, 0xbfb8aa3b, v118
	v_mul_f32_e32 v114, 0xbfb8aa3b, v128
	v_rcp_f32_e32 v116, v115
	v_add_f32_e32 v115, 1.0, v117
	v_add_f32_e32 v117, 1.0, v126
	v_mul_f32_e32 v126, 0xbfb8aa3b, v122
	v_exp_f32_e32 v127, v127
	v_mul_f32_e32 v130, 0xbfb8aa3b, v123
	v_exp_f32_e32 v114, v114
	v_exp_f32_e32 v126, v126
	v_exp_f32_e32 v131, v130
	v_mul_f32_e32 v130, 0xbfb8aa3b, v119
	v_exp_f32_e32 v132, v130
	v_add_f32_e32 v127, 1.0, v127
	v_add_f32_e32 v114, 1.0, v114
	v_add_f32_e32 v126, 1.0, v126
	v_rcp_f32_e32 v130, v127
	v_add_f32_e32 v127, 1.0, v131
	v_rcp_f32_e32 v114, v114
	v_rcp_f32_e32 v115, v115
	v_rcp_f32_e32 v117, v117
	v_rcp_f32_e32 v126, v126
	v_rcp_f32_e32 v127, v127
	v_add_f32_e32 v131, 1.0, v132
	v_rcp_f32_e32 v131, v131
	v_pk_mul_f32 v[114:115], v[128:129], v[114:115]
	v_pk_mul_f32 v[116:117], v[124:125], v[116:117]
	v_pk_mul_f32 v[132:133], v[122:123], v[126:127]
	v_pk_mul_f32 v[126:127], v[118:119], v[130:131]
	v_lshl_add_u64 v[130:131], s[62:63], 0, v[120:121]
	v_cvt_pk_bf16_f32 v114, v114, v115
	v_cvt_pk_bf16_f32 v115, v132, v133
	v_cvt_pk_bf16_f32 v116, v116, v117
	s_mov_b64 s[4:5], 0

; __device__ __forceinline__ float fast_exp(float x) { return __builtin_amdgcn_exp2f(x * LOG2E); }
; __device__ __forceinline__ float silu_f(float x) { return x * __builtin_amdgcn_rcpf(1.f + fast_exp(-x)); }
; __device__ __forceinline__ void st_bf8(bf16* p, const f32x4 a, const f32x4 b) { *(GAS v4u*)p = (v4u){pk2(a.x, a.y), pk2(a.z, a.w), pk2(b.x, b.y), pk2(b.z, b.w)}; }
;     template <int NR> __device__ __forceinline__ void rows(const int (&rowb)[NR], int fr, const float (&rstd)[NR], const f32x4 (&a)[NR][2][2], int pn, int wc, int fq) const {
;     ...
;         for (int i = 0; i < NR; ++i) {
;             const float rr = rstd[i];
; #pragma unroll
;             for (int bj = 0; bj < 2; ++bj) {
;                 f32x4 u = a[i][bj][0] * rr, v = a[i][bj][1] * rr;
;                 const size_t off = (tile_ub(rowb[i], c0b + 32 * bj, DM) + ltb) >> 1;
;                 if (blk == 0) {
; #pragma unroll
;                     for (int j = 0; j < 4; ++j) { u[j] = silu_f(u[j]); v[j] = silu_f(v[j]); }
;                     st_bf8(QH + off, u, v);
;                 } else if (blk == 1) {
; #pragma unroll
;                     for (int j = 0; j < 4; ++j) { const float s0 = __builtin_amdgcn_rcpf(1.f + fast_exp(-u[j])), s1 = __builtin_amdgcn_rcpf(1.f + fast_exp(-v[j])); u[j] = __logf(l[bj][0][j] + (1.f - l[bj][0][j]) * s0); v[j] = __logf(l[bj][1][j] + (1.f - l[bj][1][j]) * s1); }
;                     st_bf8(LOGF + off, u, v);
;                 } else if (blk == 2) {
;                     st_bf8(VH + off, u, v);
;                 } else {
; #pragma unroll
;                     for (int j = 0; j < 4; ++j) { u[j] = silu_f(u[j]); v[j] = silu_f(v[j]); }
;                     st_bf8(GH + off, u, v);
;                 }
;             }
.LBB0_326:
	s_add_i32 s4, s7, s93
	s_ashr_i32 s0, s4, 8
	s_ashr_i32 s1, s0, 31
	s_lshl_b64 s[86:87], s[0:1], 19
	s_lshl_b32 s0, s4, 7
	v_cvt_pk_bf16_f32 v117, v126, v127
	s_and_b32 s1, s0, 0x4000
	s_and_b32 s0, s0, 0x3000
	global_store_dwordx4 v[130:131], v[114:117], off sc1
	s_or_b32 s1, s86, s1
	v_pk_mul_f32 v[118:119], v[110:111], v[150:151] op_sel_hi:[1,0]
	v_pk_mul_f32 v[116:117], v[106:107], v[150:151] op_sel_hi:[1,0]
	v_or_b32_e32 v106, s0, v170
	v_pk_mul_f32 v[114:115], v[112:113], v[150:151] op_sel_hi:[1,0]
	v_pk_mul_f32 v[112:113], v[108:109], v[150:151] op_sel_hi:[1,0]
	v_or_b32_e32 v110, s1, v106
	v_mov_b32_e32 v111, s87
	s_and_b64 vcc, exec, s[12:13]
	s_mov_b64 s[4:5], -1
	s_cbranch_vccnz .LBB0_336
	s_and_b64 vcc, exec, s[10:11]
	s_cbranch_vccnz .LBB0_333
	s_andn2_b64 vcc, exec, s[82:83]
	s_cbranch_vccnz .LBB0_330
	v_mul_f32_e32 v107, 0xbfb8aa3b, v116
	v_mul_f32_e32 v108, 0xbfb8aa3b, v119
	v_exp_f32_e32 v107, v107
	v_exp_f32_e32 v109, v108
	v_mul_f32_e32 v108, 0xbfb8aa3b, v117
	v_exp_f32_e32 v120, v108
	v_add_f32_e32 v107, 1.0, v107
	v_mul_f32_e32 v121, 0xbfb8aa3b, v112
	v_mul_f32_e32 v106, 0xbfb8aa3b, v118
	v_rcp_f32_e32 v108, v107
	v_add_f32_e32 v107, 1.0, v109
	v_add_f32_e32 v109, 1.0, v120
	v_mul_f32_e32 v120, 0xbfb8aa3b, v114
	v_exp_f32_e32 v121, v121
	v_mul_f32_e32 v122, 0xbfb8aa3b, v115
	v_exp_f32_e32 v106, v106
	v_exp_f32_e32 v120, v120
	v_exp_f32_e32 v123, v122
	v_mul_f32_e32 v122, 0xbfb8aa3b, v113
	v_exp_f32_e32 v124, v122
	v_add_f32_e32 v121, 1.0, v121
	v_add_f32_e32 v106, 1.0, v106
	v_add_f32_e32 v120, 1.0, v120
	v_rcp_f32_e32 v122, v121
	v_add_f32_e32 v121, 1.0, v123
	v_rcp_f32_e32 v106, v106
	v_rcp_f32_e32 v107, v107
	v_rcp_f32_e32 v109, v109
	v_rcp_f32_e32 v120, v120
	v_rcp_f32_e32 v121, v121
	v_add_f32_e32 v123, 1.0, v124
	v_rcp_f32_e32 v123, v123
	v_pk_mul_f32 v[106:107], v[118:119], v[106:107]
	v_pk_mul_f32 v[108:109], v[116:117], v[108:109]
	v_pk_mul_f32 v[124:125], v[114:115], v[120:121]
	v_pk_mul_f32 v[120:121], v[112:113], v[122:123]
	v_lshl_add_u64 v[122:123], s[62:63], 0, v[110:111]
	v_cvt_pk_bf16_f32 v106, v106, v107
	v_cvt_pk_bf16_f32 v107, v124, v125
	v_cvt_pk_bf16_f32 v108, v108, v109
	s_mov_b64 s[4:5], 0

; __device__ __forceinline__ float fast_exp(float x) { return __builtin_amdgcn_exp2f(x * LOG2E); }
; __device__ __forceinline__ float silu_f(float x) { return x * __builtin_amdgcn_rcpf(1.f + fast_exp(-x)); }
; __device__ __forceinline__ void st_bf8(bf16* p, const f32x4 a, const f32x4 b) { *(GAS v4u*)p = (v4u){pk2(a.x, a.y), pk2(a.z, a.w), pk2(b.x, b.y), pk2(b.z, b.w)}; }
;     template <int NR> __device__ __forceinline__ void rows(const int (&rowb)[NR], int fr, const float (&rstd)[NR], const f32x4 (&a)[NR][2][2], int pn, int wc, int fq) const {
;     ...
;         for (int i = 0; i < NR; ++i) {
;             const float rr = rstd[i];
; #pragma unroll
;             for (int bj = 0; bj < 2; ++bj) {
;                 f32x4 u = a[i][bj][0] * rr, v = a[i][bj][1] * rr;
;                 const size_t off = (tile_ub(rowb[i], c0b + 32 * bj, DM) + ltb) >> 1;
;                 if (blk == 0) {
; #pragma unroll
;                     for (int j = 0; j < 4; ++j) { u[j] = silu_f(u[j]); v[j] = silu_f(v[j]); }
;                     st_bf8(QH + off, u, v);
;                 } else if (blk == 1) {
; #pragma unroll
;                     for (int j = 0; j < 4; ++j) { const float s0 = __builtin_amdgcn_rcpf(1.f + fast_exp(-u[j])), s1 = __builtin_amdgcn_rcpf(1.f + fast_exp(-v[j])); u[j] = __logf(l[bj][0][j] + (1.f - l[bj][0][j]) * s0); v[j] = __logf(l[bj][1][j] + (1.f - l[bj][1][j]) * s1); }
;                     st_bf8(LOGF + off, u, v);
;                 } else if (blk == 2) {
;                     st_bf8(VH + off, u, v);
;                 } else {
; #pragma unroll
;                     for (int j = 0; j < 4; ++j) { u[j] = silu_f(u[j]); v[j] = silu_f(v[j]); }
;                     st_bf8(GH + off, u, v);
;                 }
;             }
.LBB0_338:
	s_nop 0
	v_cvt_pk_bf16_f32 v109, v120, v121
	v_mov_b32_e32 v114, v150
	v_mov_b32_e32 v115, v150
	global_store_dwordx4 v[122:123], v[106:109], off sc1
	v_pk_mul_f32 v[112:113], v[102:103], v[114:115]
	s_and_b64 vcc, exec, s[12:13]
	v_mov_b32_e32 v108, v150
	v_mov_b32_e32 v109, v150
	v_pk_mul_f32 v[106:107], v[104:105], v[108:109]
	v_pk_mul_f32 v[102:103], v[100:101], v[108:109]
	v_pk_mul_f32 v[108:109], v[98:99], v[114:115]
	v_or_b32_e32 v104, 0x400, v110
	v_mov_b32_e32 v105, s87
	s_mov_b64 s[4:5], -1
	s_cbranch_vccnz .LBB0_348
	s_and_b64 vcc, exec, s[10:11]
	s_cbranch_vccnz .LBB0_345
	s_andn2_b64 vcc, exec, s[82:83]
	s_cbranch_vccnz .LBB0_342
	v_mul_f32_e32 v99, 0xbfb8aa3b, v108
	v_mul_f32_e32 v100, 0xbfb8aa3b, v113
	v_exp_f32_e32 v99, v99
	v_exp_f32_e32 v101, v100
	v_mul_f32_e32 v100, 0xbfb8aa3b, v109
	v_exp_f32_e32 v110, v100
	v_add_f32_e32 v99, 1.0, v99
	v_mul_f32_e32 v111, 0xbfb8aa3b, v102
	v_mul_f32_e32 v98, 0xbfb8aa3b, v112
	v_rcp_f32_e32 v100, v99
	v_add_f32_e32 v99, 1.0, v101
	v_add_f32_e32 v101, 1.0, v110
	v_mul_f32_e32 v110, 0xbfb8aa3b, v106
	v_exp_f32_e32 v111, v111
	v_mul_f32_e32 v114, 0xbfb8aa3b, v107
	v_exp_f32_e32 v98, v98
	v_exp_f32_e32 v110, v110
	v_exp_f32_e32 v115, v114
	v_mul_f32_e32 v114, 0xbfb8aa3b, v103
	v_exp_f32_e32 v116, v114
	v_add_f32_e32 v111, 1.0, v111
	v_add_f32_e32 v98, 1.0, v98
	v_add_f32_e32 v110, 1.0, v110
	v_rcp_f32_e32 v114, v111
	v_add_f32_e32 v111, 1.0, v115
	v_rcp_f32_e32 v98, v98
	v_rcp_f32_e32 v99, v99
	v_rcp_f32_e32 v101, v101
	v_rcp_f32_e32 v110, v110
	v_rcp_f32_e32 v111, v111
	v_add_f32_e32 v115, 1.0, v116
	v_rcp_f32_e32 v115, v115
	v_pk_mul_f32 v[98:99], v[112:113], v[98:99]
	v_pk_mul_f32 v[100:101], v[108:109], v[100:101]
	v_pk_mul_f32 v[116:117], v[106:107], v[110:111]
	v_pk_mul_f32 v[110:111], v[102:103], v[114:115]
	v_lshl_add_u64 v[114:115], s[62:63], 0, v[104:105]
	v_cvt_pk_bf16_f32 v98, v98, v99
	v_cvt_pk_bf16_f32 v99, v116, v117
	v_cvt_pk_bf16_f32 v100, v100, v101
	s_mov_b64 s[4:5], 0

; __device__ __forceinline__ float fast_exp(float x) { return __builtin_amdgcn_exp2f(x * LOG2E); }
; __device__ __forceinline__ float silu_f(float x) { return x * __builtin_amdgcn_rcpf(1.f + fast_exp(-x)); }
; __device__ __forceinline__ void st_bf8(bf16* p, const f32x4 a, const f32x4 b) { *(GAS v4u*)p = (v4u){pk2(a.x, a.y), pk2(a.z, a.w), pk2(b.x, b.y), pk2(b.z, b.w)}; }
;     template <int NR> __device__ __forceinline__ void rows(const int (&rowb)[NR], int fr, const float (&rstd)[NR], const f32x4 (&a)[NR][2][2], int pn, int wc, int fq) const {
;     ...
;         for (int i = 0; i < NR; ++i) {
;             const float rr = rstd[i];
; #pragma unroll
;             for (int bj = 0; bj < 2; ++bj) {
;                 f32x4 u = a[i][bj][0] * rr, v = a[i][bj][1] * rr;
;                 const size_t off = (tile_ub(rowb[i], c0b + 32 * bj, DM) + ltb) >> 1;
;                 if (blk == 0) {
; #pragma unroll
;                     for (int j = 0; j < 4; ++j) { u[j] = silu_f(u[j]); v[j] = silu_f(v[j]); }
;                     st_bf8(QH + off, u, v);
;                 } else if (blk == 1) {
; #pragma unroll
;                     for (int j = 0; j < 4; ++j) { const float s0 = __builtin_amdgcn_rcpf(1.f + fast_exp(-u[j])), s1 = __builtin_amdgcn_rcpf(1.f + fast_exp(-v[j])); u[j] = __logf(l[bj][0][j] + (1.f - l[bj][0][j]) * s0); v[j] = __logf(l[bj][1][j] + (1.f - l[bj][1][j]) * s1); }
;                     st_bf8(LOGF + off, u, v);
;                 } else if (blk == 2) {
;                     st_bf8(VH + off, u, v);
;                 } else {
; #pragma unroll
;                     for (int j = 0; j < 4; ++j) { u[j] = silu_f(u[j]); v[j] = silu_f(v[j]); }
;                     st_bf8(GH + off, u, v);
;                 }
;             }
.LBB0_350:
	s_add_i32 s7, s7, s46
	s_ashr_i32 s0, s7, 8
	s_ashr_i32 s1, s0, 31
	v_cvt_pk_bf16_f32 v101, v110, v111
	s_lshl_b64 s[86:87], s[0:1], 19
	s_lshl_b32 s0, s7, 7
	global_store_dwordx4 v[114:115], v[98:101], off sc1
	s_and_b32 s1, s0, 0x4000
	s_and_b32 s0, s0, 0x3800
	v_mov_b32_e32 v100, v151
	v_pk_mul_f32 v[98:99], v[88:89], v[100:101] op_sel_hi:[1,0]
	v_pk_mul_f32 v[102:103], v[86:87], v[100:101] op_sel_hi:[1,0]
	v_pk_mul_f32 v[88:89], v[84:85], v[100:101] op_sel_hi:[1,0]
	v_pk_mul_f32 v[100:101], v[82:83], v[100:101] op_sel_hi:[1,0]
	s_or_b32 s1, s86, s1
	v_or_b32_e32 v82, s0, v170
	v_or_b32_e32 v86, s1, v82
	v_mov_b32_e32 v87, s87
	s_and_b64 vcc, exec, s[12:13]
	s_mov_b64 s[4:5], -1
	s_cbranch_vccnz .LBB0_360
	s_and_b64 vcc, exec, s[10:11]
	s_cbranch_vccnz .LBB0_357
	s_andn2_b64 vcc, exec, s[82:83]
	s_cbranch_vccnz .LBB0_354
	v_mul_f32_e32 v83, 0xbfb8aa3b, v100
	v_mul_f32_e32 v84, 0xbfb8aa3b, v103
	v_exp_f32_e32 v83, v83
	v_exp_f32_e32 v85, v84
	v_mul_f32_e32 v84, 0xbfb8aa3b, v101
	v_exp_f32_e32 v104, v84
	v_add_f32_e32 v83, 1.0, v83
	v_mul_f32_e32 v105, 0xbfb8aa3b, v88
	v_mul_f32_e32 v82, 0xbfb8aa3b, v102
	v_rcp_f32_e32 v84, v83
	v_add_f32_e32 v83, 1.0, v85
	v_add_f32_e32 v85, 1.0, v104
	v_mul_f32_e32 v104, 0xbfb8aa3b, v98
	v_exp_f32_e32 v105, v105
	v_mul_f32_e32 v106, 0xbfb8aa3b, v99
	v_exp_f32_e32 v82, v82
	v_exp_f32_e32 v104, v104
	v_exp_f32_e32 v107, v106
	v_mul_f32_e32 v106, 0xbfb8aa3b, v89
	v_exp_f32_e32 v108, v106
	v_add_f32_e32 v105, 1.0, v105
	v_add_f32_e32 v82, 1.0, v82
	v_add_f32_e32 v104, 1.0, v104
	v_rcp_f32_e32 v106, v105
	v_add_f32_e32 v105, 1.0, v107
	v_rcp_f32_e32 v82, v82
	v_rcp_f32_e32 v83, v83
	v_rcp_f32_e32 v85, v85
	v_rcp_f32_e32 v104, v104
	v_rcp_f32_e32 v105, v105
	v_add_f32_e32 v107, 1.0, v108
	v_rcp_f32_e32 v107, v107
	v_pk_mul_f32 v[82:83], v[102:103], v[82:83]
	v_pk_mul_f32 v[84:85], v[100:101], v[84:85]
	v_pk_mul_f32 v[108:109], v[98:99], v[104:105]
	v_pk_mul_f32 v[104:105], v[88:89], v[106:107]
	v_lshl_add_u64 v[106:107], s[62:63], 0, v[86:87]
	v_cvt_pk_bf16_f32 v82, v82, v83
	v_cvt_pk_bf16_f32 v83, v108, v109
	v_cvt_pk_bf16_f32 v84, v84, v85
	s_mov_b64 s[4:5], 0

; __device__ __forceinline__ float fast_exp(float x) { return __builtin_amdgcn_exp2f(x * LOG2E); }
; __device__ __forceinline__ float silu_f(float x) { return x * __builtin_amdgcn_rcpf(1.f + fast_exp(-x)); }
; __device__ __forceinline__ void st_bf8(bf16* p, const f32x4 a, const f32x4 b) { *(GAS v4u*)p = (v4u){pk2(a.x, a.y), pk2(a.z, a.w), pk2(b.x, b.y), pk2(b.z, b.w)}; }
;     template <int NR> __device__ __forceinline__ void rows(const int (&rowb)[NR], int fr, const float (&rstd)[NR], const f32x4 (&a)[NR][2][2], int pn, int wc, int fq) const {
;     ...
;         for (int i = 0; i < NR; ++i) {
;             const float rr = rstd[i];
; #pragma unroll
;             for (int bj = 0; bj < 2; ++bj) {
;                 f32x4 u = a[i][bj][0] * rr, v = a[i][bj][1] * rr;
;                 const size_t off = (tile_ub(rowb[i], c0b + 32 * bj, DM) + ltb) >> 1;
;                 if (blk == 0) {
; #pragma unroll
;                     for (int j = 0; j < 4; ++j) { u[j] = silu_f(u[j]); v[j] = silu_f(v[j]); }
;                     st_bf8(QH + off, u, v);
;                 } else if (blk == 1) {
; #pragma unroll
;                     for (int j = 0; j < 4; ++j) { const float s0 = __builtin_amdgcn_rcpf(1.f + fast_exp(-u[j])), s1 = __builtin_amdgcn_rcpf(1.f + fast_exp(-v[j])); u[j] = __logf(l[bj][0][j] + (1.f - l[bj][0][j]) * s0); v[j] = __logf(l[bj][1][j] + (1.f - l[bj][1][j]) * s1); }
;                     st_bf8(LOGF + off, u, v);
;                 } else if (blk == 2) {
;                     st_bf8(VH + off, u, v);
;                 } else {
; #pragma unroll
;                     for (int j = 0; j < 4; ++j) { u[j] = silu_f(u[j]); v[j] = silu_f(v[j]); }
;                     st_bf8(GH + off, u, v);
;                 }
;             }
.LBB0_362:
	v_cvt_pk_bf16_f32 v85, v104, v105
	v_mov_b32_e32 v150, v151
	global_store_dwordx4 v[106:107], v[82:85], off sc1
	v_pk_mul_f32 v[88:89], v[70:71], v[150:151]
	s_and_b64 vcc, exec, s[12:13]
	v_mov_b32_e32 v84, v151
	v_mov_b32_e32 v85, v151
	v_pk_mul_f32 v[82:83], v[72:73], v[84:85]
	v_pk_mul_f32 v[70:71], v[68:69], v[84:85]
	v_pk_mul_f32 v[84:85], v[66:67], v[150:151]
	v_or_b32_e32 v72, 0x400, v86
	v_mov_b32_e32 v73, s87
	s_mov_b64 s[4:5], -1
	s_cbranch_vccnz .LBB0_372
	s_and_b64 vcc, exec, s[10:11]
	s_cbranch_vccnz .LBB0_369
	s_andn2_b64 vcc, exec, s[82:83]
	s_cbranch_vccnz .LBB0_366
	v_mul_f32_e32 v67, 0xbfb8aa3b, v84
	v_mul_f32_e32 v68, 0xbfb8aa3b, v89
	v_exp_f32_e32 v67, v67
	v_exp_f32_e32 v69, v68
	v_mul_f32_e32 v68, 0xbfb8aa3b, v85
	v_exp_f32_e32 v86, v68
	v_add_f32_e32 v67, 1.0, v67
	v_mul_f32_e32 v87, 0xbfb8aa3b, v70
	v_mul_f32_e32 v66, 0xbfb8aa3b, v88
	v_rcp_f32_e32 v68, v67
	v_add_f32_e32 v67, 1.0, v69
	v_add_f32_e32 v69, 1.0, v86
	v_mul_f32_e32 v86, 0xbfb8aa3b, v82
	v_exp_f32_e32 v87, v87
	s_waitcnt vmcnt(0)
	v_mul_f32_e32 v90, 0xbfb8aa3b, v83
	v_exp_f32_e32 v66, v66
	v_exp_f32_e32 v86, v86
	v_exp_f32_e32 v91, v90
	v_mul_f32_e32 v90, 0xbfb8aa3b, v71
	v_exp_f32_e32 v92, v90
	v_add_f32_e32 v87, 1.0, v87
	v_add_f32_e32 v66, 1.0, v66
	v_add_f32_e32 v86, 1.0, v86
	v_rcp_f32_e32 v90, v87
	v_add_f32_e32 v87, 1.0, v91
	v_rcp_f32_e32 v66, v66
	v_rcp_f32_e32 v67, v67
	v_rcp_f32_e32 v69, v69
	v_rcp_f32_e32 v86, v86
	v_rcp_f32_e32 v87, v87
	v_add_f32_e32 v91, 1.0, v92
	v_rcp_f32_e32 v91, v91
	v_pk_mul_f32 v[66:67], v[88:89], v[66:67]
	v_pk_mul_f32 v[68:69], v[84:85], v[68:69]
	v_pk_mul_f32 v[92:93], v[82:83], v[86:87]
	v_pk_mul_f32 v[86:87], v[70:71], v[90:91]
	v_lshl_add_u64 v[90:91], s[62:63], 0, v[72:73]
	v_cvt_pk_bf16_f32 v66, v66, v67
	v_cvt_pk_bf16_f32 v67, v92, v93
	v_cvt_pk_bf16_f32 v68, v68, v69
	s_mov_b64 s[4:5], 0

; __device__ __forceinline__ unsigned lane_tb(int fr, int fq) { return (unsigned)((fr * 64 + fq * 16) ^ ((fr >> 3) << 5)); }
;     template <int NR> __device__ __forceinline__ void rows(const int (&rowb)[NR], int fr, const float (&rstd)[NR], const f32x4 (&a)[NR][2][2], int pn, int wc, int fq) const {
;         const int blk = pn >> 2, c0b = ((pn & 3) << 8) + 64 * wc, c0 = c0b + 8 * fq; const unsigned ltb = lane_tb(fr, fq);
;         f32x4 l[2][2];
;         if (blk == 1) {
; #pragma unroll
;             for (int bj = 0; bj < 2; ++bj) { l[bj][0] = *(const f32x4*)(lb + c0 + 32 * bj); l[bj][1] = *(const f32x4*)(lb + c0 + 32 * bj + 4); }
;         }
;     __device__ __forceinline__ void operator()(const f32x4 (&acc)[2][2][4][2], const pg8::Unit& u, int wr, int wc, int fr, int fq, PG8_LAS unsigned char* tabb) const {
;     ...
;             int row[4]; f32x4 a[4][2][2]; float rr[4];
; #pragma unroll
;             for (int m = 0; m < 4; ++m) { const int rl = ai * 128 + wr * 64 + m * 16; row[m] = u.pm * 256 + rl; rr[m] = rsp ? tab[rl + fr] : 1.f;
.LBB0_374:
	v_cvt_pk_bf16_f32 v69, v86, v87
	s_waitcnt vmcnt(0)
	global_store_dwordx4 v[90:91], v[66:69], off sc1
	ds_read2_b32 v[84:85], v172 offset0:128 offset1:144
	ds_read2_b32 v[82:83], v172 offset0:160 offset1:176
	v_mov_b32_e32 v78, 0
	s_andn2_b64 vcc, exec, s[84:85]
	v_mov_b32_e32 v79, 0
	v_mov_b32_e32 v80, 0
	v_mov_b32_e32 v81, 0
	v_mov_b32_e32 v74, 0
	v_mov_b32_e32 v75, 0
	v_mov_b32_e32 v76, 0
	v_mov_b32_e32 v77, 0
	v_mov_b32_e32 v70, 0
	v_mov_b32_e32 v71, 0
	v_mov_b32_e32 v72, 0
	v_mov_b32_e32 v73, 0
	v_mov_b32_e32 v66, 0
	v_mov_b32_e32 v67, 0
	v_mov_b32_e32 v68, 0
	v_mov_b32_e32 v69, 0
	s_cbranch_vccnz .LBB0_376
	global_load_dwordx4 v[78:81], v171, s[56:57]
	global_load_dwordx4 v[74:77], v171, s[56:57] offset:16
	global_load_dwordx4 v[70:73], v171, s[56:57] offset:128
	global_load_dwordx4 v[66:69], v171, s[56:57] offset:144

; __device__ __forceinline__ float fast_exp(float x) { return __builtin_amdgcn_exp2f(x * LOG2E); }
; __device__ __forceinline__ float silu_f(float x) { return x * __builtin_amdgcn_rcpf(1.f + fast_exp(-x)); }
; __device__ __forceinline__ void st_bf8(bf16* p, const f32x4 a, const f32x4 b) { *(GAS v4u*)p = (v4u){pk2(a.x, a.y), pk2(a.z, a.w), pk2(b.x, b.y), pk2(b.z, b.w)}; }
;     template <int NR> __device__ __forceinline__ void rows(const int (&rowb)[NR], int fr, const float (&rstd)[NR], const f32x4 (&a)[NR][2][2], int pn, int wc, int fq) const {
;     ...
;         for (int i = 0; i < NR; ++i) {
;             const float rr = rstd[i];
; #pragma unroll
;             for (int bj = 0; bj < 2; ++bj) {
;                 f32x4 u = a[i][bj][0] * rr, v = a[i][bj][1] * rr;
;                 const size_t off = (tile_ub(rowb[i], c0b + 32 * bj, DM) + ltb) >> 1;
;                 if (blk == 0) {
; #pragma unroll
;                     for (int j = 0; j < 4; ++j) { u[j] = silu_f(u[j]); v[j] = silu_f(v[j]); }
;                     st_bf8(QH + off, u, v);
;                 } else if (blk == 1) {
; #pragma unroll
;                     for (int j = 0; j < 4; ++j) { const float s0 = __builtin_amdgcn_rcpf(1.f + fast_exp(-u[j])), s1 = __builtin_amdgcn_rcpf(1.f + fast_exp(-v[j])); u[j] = __logf(l[bj][0][j] + (1.f - l[bj][0][j]) * s0); v[j] = __logf(l[bj][1][j] + (1.f - l[bj][1][j]) * s1); }
;                     st_bf8(LOGF + off, u, v);
;                 } else if (blk == 2) {
;                     st_bf8(VH + off, u, v);
;                 } else {
; #pragma unroll
;                     for (int j = 0; j < 4; ++j) { u[j] = silu_f(u[j]); v[j] = silu_f(v[j]); }
;                     st_bf8(GH + off, u, v);
;                 }
;             }
.LBB0_388:
	s_nop 0
	v_cvt_pk_bf16_f32 v61, v92, v93
	v_mov_b32_e32 v86, v84
	v_mov_b32_e32 v87, v84
	global_store_dwordx4 v[94:95], v[58:61], off sc1
	v_pk_mul_f32 v[64:65], v[54:55], v[86:87]
	s_and_b64 vcc, exec, s[12:13]
	v_mov_b32_e32 v60, v84
	v_mov_b32_e32 v61, v84
	v_pk_mul_f32 v[58:59], v[56:57], v[60:61]
	v_pk_mul_f32 v[54:55], v[52:53], v[60:61]
	v_pk_mul_f32 v[60:61], v[50:51], v[86:87]
	v_or_b32_e32 v56, 0x400, v62
	v_mov_b32_e32 v57, s85
	s_mov_b64 s[4:5], -1
	s_cbranch_vccnz .LBB0_398
	s_and_b64 vcc, exec, s[10:11]
	s_cbranch_vccnz .LBB0_395
	s_andn2_b64 vcc, exec, s[82:83]
	s_cbranch_vccnz .LBB0_392
	v_mul_f32_e32 v51, 0xbfb8aa3b, v60
	v_mul_f32_e32 v52, 0xbfb8aa3b, v65
	v_exp_f32_e32 v51, v51
	v_exp_f32_e32 v53, v52
	v_mul_f32_e32 v52, 0xbfb8aa3b, v61
	v_exp_f32_e32 v62, v52
	v_add_f32_e32 v51, 1.0, v51
	v_mul_f32_e32 v63, 0xbfb8aa3b, v54
	v_mul_f32_e32 v50, 0xbfb8aa3b, v64
	v_rcp_f32_e32 v52, v51
	v_add_f32_e32 v51, 1.0, v53
	v_add_f32_e32 v53, 1.0, v62
	v_mul_f32_e32 v62, 0xbfb8aa3b, v58
	v_exp_f32_e32 v63, v63
	v_mul_f32_e32 v84, 0xbfb8aa3b, v59
	v_exp_f32_e32 v50, v50
	v_exp_f32_e32 v62, v62
	v_exp_f32_e32 v84, v84
	v_mul_f32_e32 v86, 0xbfb8aa3b, v55
	v_exp_f32_e32 v87, v86
	v_add_f32_e32 v63, 1.0, v63
	v_add_f32_e32 v50, 1.0, v50
	v_add_f32_e32 v62, 1.0, v62
	v_rcp_f32_e32 v86, v63
	v_add_f32_e32 v63, 1.0, v84
	v_rcp_f32_e32 v50, v50
	v_rcp_f32_e32 v51, v51
	v_rcp_f32_e32 v53, v53
	v_rcp_f32_e32 v62, v62
	v_rcp_f32_e32 v63, v63
	v_add_f32_e32 v84, 1.0, v87
	v_rcp_f32_e32 v87, v84
	v_pk_mul_f32 v[50:51], v[64:65], v[50:51]
	v_pk_mul_f32 v[52:53], v[60:61], v[52:53]
	v_pk_mul_f32 v[88:89], v[58:59], v[62:63]
	v_pk_mul_f32 v[62:63], v[54:55], v[86:87]
	v_lshl_add_u64 v[86:87], s[62:63], 0, v[56:57]
	v_cvt_pk_bf16_f32 v50, v50, v51
	v_cvt_pk_bf16_f32 v51, v88, v89
	v_cvt_pk_bf16_f32 v52, v52, v53
	s_mov_b64 s[4:5], 0

; __device__ __forceinline__ float fast_exp(float x) { return __builtin_amdgcn_exp2f(x * LOG2E); }
; __device__ __forceinline__ float silu_f(float x) { return x * __builtin_amdgcn_rcpf(1.f + fast_exp(-x)); }
; __device__ __forceinline__ void st_bf8(bf16* p, const f32x4 a, const f32x4 b) { *(GAS v4u*)p = (v4u){pk2(a.x, a.y), pk2(a.z, a.w), pk2(b.x, b.y), pk2(b.z, b.w)}; }
;     template <int NR> __device__ __forceinline__ void rows(const int (&rowb)[NR], int fr, const float (&rstd)[NR], const f32x4 (&a)[NR][2][2], int pn, int wc, int fq) const {
;     ...
;         for (int i = 0; i < NR; ++i) {
;             const float rr = rstd[i];
; #pragma unroll
;             for (int bj = 0; bj < 2; ++bj) {
;                 f32x4 u = a[i][bj][0] * rr, v = a[i][bj][1] * rr;
;                 const size_t off = (tile_ub(rowb[i], c0b + 32 * bj, DM) + ltb) >> 1;
;                 if (blk == 0) {
; #pragma unroll
;                     for (int j = 0; j < 4; ++j) { u[j] = silu_f(u[j]); v[j] = silu_f(v[j]); }
;                     st_bf8(QH + off, u, v);
;                 } else if (blk == 1) {
; #pragma unroll
;                     for (int j = 0; j < 4; ++j) { const float s0 = __builtin_amdgcn_rcpf(1.f + fast_exp(-u[j])), s1 = __builtin_amdgcn_rcpf(1.f + fast_exp(-v[j])); u[j] = __logf(l[bj][0][j] + (1.f - l[bj][0][j]) * s0); v[j] = __logf(l[bj][1][j] + (1.f - l[bj][1][j]) * s1); }
;                     st_bf8(LOGF + off, u, v);
;                 } else if (blk == 2) {
;                     st_bf8(VH + off, u, v);
;                 } else {
; #pragma unroll
;                     for (int j = 0; j < 4; ++j) { u[j] = silu_f(u[j]); v[j] = silu_f(v[j]); }
;                     st_bf8(GH + off, u, v);
;                 }
;             }
.LBB0_400:
	s_add_i32 s4, s6, 0x90
	s_ashr_i32 s0, s4, 8
	s_ashr_i32 s1, s0, 31
	v_cvt_pk_bf16_f32 v53, v62, v63
	s_lshl_b64 s[84:85], s[0:1], 19
	s_lshl_b32 s0, s4, 7
	global_store_dwordx4 v[86:87], v[50:53], off sc1
	s_and_b32 s1, s0, 0x4000
	s_and_b32 s0, s0, 0x2800
	v_mov_b32_e32 v52, v85
	v_pk_mul_f32 v[50:51], v[48:49], v[52:53] op_sel_hi:[1,0]
	v_pk_mul_f32 v[54:55], v[46:47], v[52:53] op_sel_hi:[1,0]
	v_pk_mul_f32 v[48:49], v[44:45], v[52:53] op_sel_hi:[1,0]
	v_pk_mul_f32 v[52:53], v[42:43], v[52:53] op_sel_hi:[1,0]
	s_or_b32 s1, s84, s1
	v_or_b32_e32 v42, s0, v170
	v_or_b32_e32 v46, s1, v42
	v_mov_b32_e32 v47, s85
	s_and_b64 vcc, exec, s[12:13]
	s_mov_b64 s[4:5], -1
	s_cbranch_vccnz .LBB0_410
	s_and_b64 vcc, exec, s[10:11]
	s_cbranch_vccnz .LBB0_407
	s_andn2_b64 vcc, exec, s[82:83]
	s_cbranch_vccnz .LBB0_404
	v_mul_f32_e32 v43, 0xbfb8aa3b, v52
	v_mul_f32_e32 v44, 0xbfb8aa3b, v55
	v_exp_f32_e32 v43, v43
	v_exp_f32_e32 v45, v44
	v_mul_f32_e32 v44, 0xbfb8aa3b, v53
	v_exp_f32_e32 v56, v44
	v_add_f32_e32 v43, 1.0, v43
	v_mul_f32_e32 v57, 0xbfb8aa3b, v48
	v_mul_f32_e32 v42, 0xbfb8aa3b, v54
	v_rcp_f32_e32 v44, v43
	v_add_f32_e32 v43, 1.0, v45
	v_add_f32_e32 v45, 1.0, v56
	v_mul_f32_e32 v56, 0xbfb8aa3b, v50
	v_exp_f32_e32 v57, v57
	v_mul_f32_e32 v58, 0xbfb8aa3b, v51
	v_exp_f32_e32 v42, v42
	v_exp_f32_e32 v56, v56
	v_exp_f32_e32 v59, v58
	v_mul_f32_e32 v58, 0xbfb8aa3b, v49
	v_exp_f32_e32 v60, v58
	v_add_f32_e32 v57, 1.0, v57
	v_add_f32_e32 v42, 1.0, v42
	v_add_f32_e32 v56, 1.0, v56
	v_rcp_f32_e32 v58, v57
	v_add_f32_e32 v57, 1.0, v59
	v_rcp_f32_e32 v42, v42
	v_rcp_f32_e32 v43, v43
	v_rcp_f32_e32 v45, v45
	v_rcp_f32_e32 v56, v56
	v_rcp_f32_e32 v57, v57
	v_add_f32_e32 v59, 1.0, v60
	v_rcp_f32_e32 v59, v59
	v_pk_mul_f32 v[42:43], v[54:55], v[42:43]
	v_pk_mul_f32 v[44:45], v[52:53], v[44:45]
	v_pk_mul_f32 v[60:61], v[50:51], v[56:57]
	v_pk_mul_f32 v[56:57], v[48:49], v[58:59]
	v_lshl_add_u64 v[58:59], s[62:63], 0, v[46:47]
	v_cvt_pk_bf16_f32 v42, v42, v43
	v_cvt_pk_bf16_f32 v43, v60, v61
	v_cvt_pk_bf16_f32 v44, v44, v45
	s_mov_b64 s[4:5], 0

; __device__ __forceinline__ float fast_exp(float x) { return __builtin_amdgcn_exp2f(x * LOG2E); }
; __device__ __forceinline__ float silu_f(float x) { return x * __builtin_amdgcn_rcpf(1.f + fast_exp(-x)); }
; __device__ __forceinline__ void st_bf8(bf16* p, const f32x4 a, const f32x4 b) { *(GAS v4u*)p = (v4u){pk2(a.x, a.y), pk2(a.z, a.w), pk2(b.x, b.y), pk2(b.z, b.w)}; }
;     template <int NR> __device__ __forceinline__ void rows(const int (&rowb)[NR], int fr, const float (&rstd)[NR], const f32x4 (&a)[NR][2][2], int pn, int wc, int fq) const {
;     ...
;         for (int i = 0; i < NR; ++i) {
;             const float rr = rstd[i];
; #pragma unroll
;             for (int bj = 0; bj < 2; ++bj) {
;                 f32x4 u = a[i][bj][0] * rr, v = a[i][bj][1] * rr;
;                 const size_t off = (tile_ub(rowb[i], c0b + 32 * bj, DM) + ltb) >> 1;
;                 if (blk == 0) {
; #pragma unroll
;                     for (int j = 0; j < 4; ++j) { u[j] = silu_f(u[j]); v[j] = silu_f(v[j]); }
;                     st_bf8(QH + off, u, v);
;                 } else if (blk == 1) {
; #pragma unroll
;                     for (int j = 0; j < 4; ++j) { const float s0 = __builtin_amdgcn_rcpf(1.f + fast_exp(-u[j])), s1 = __builtin_amdgcn_rcpf(1.f + fast_exp(-v[j])); u[j] = __logf(l[bj][0][j] + (1.f - l[bj][0][j]) * s0); v[j] = __logf(l[bj][1][j] + (1.f - l[bj][1][j]) * s1); }
;                     st_bf8(LOGF + off, u, v);
;                 } else if (blk == 2) {
;                     st_bf8(VH + off, u, v);
;                 } else {
; #pragma unroll
;                     for (int j = 0; j < 4; ++j) { u[j] = silu_f(u[j]); v[j] = silu_f(v[j]); }
;                     st_bf8(GH + off, u, v);
;                 }
.LBB0_412:
	s_nop 0
	v_cvt_pk_bf16_f32 v45, v56, v57
	v_mov_b32_e32 v84, v85
	global_store_dwordx4 v[58:59], v[42:45], off sc1
	v_pk_mul_f32 v[48:49], v[38:39], v[84:85]
	s_and_b64 vcc, exec, s[12:13]
	v_mov_b32_e32 v44, v85
	v_mov_b32_e32 v45, v85
	v_pk_mul_f32 v[42:43], v[40:41], v[44:45]
	v_pk_mul_f32 v[38:39], v[36:37], v[44:45]
	v_pk_mul_f32 v[44:45], v[34:35], v[84:85]
	v_or_b32_e32 v40, 0x400, v46
	v_mov_b32_e32 v41, s85
	s_mov_b64 s[4:5], -1
	s_cbranch_vccnz .LBB0_422
	s_and_b64 vcc, exec, s[10:11]
	s_cbranch_vccnz .LBB0_419
	s_andn2_b64 vcc, exec, s[82:83]
	s_cbranch_vccnz .LBB0_416
	v_mul_f32_e32 v35, 0xbfb8aa3b, v44
	v_mul_f32_e32 v36, 0xbfb8aa3b, v49
	v_exp_f32_e32 v35, v35
	v_exp_f32_e32 v37, v36
	v_mul_f32_e32 v36, 0xbfb8aa3b, v45
	v_exp_f32_e32 v46, v36
	v_add_f32_e32 v35, 1.0, v35
	v_mul_f32_e32 v47, 0xbfb8aa3b, v38
	v_mul_f32_e32 v34, 0xbfb8aa3b, v48
	v_rcp_f32_e32 v36, v35
	v_add_f32_e32 v35, 1.0, v37
	v_add_f32_e32 v37, 1.0, v46
	v_mul_f32_e32 v46, 0xbfb8aa3b, v42
	v_exp_f32_e32 v47, v47
	v_mul_f32_e32 v50, 0xbfb8aa3b, v43
	v_exp_f32_e32 v34, v34
	v_exp_f32_e32 v46, v46
	v_exp_f32_e32 v51, v50
	v_mul_f32_e32 v50, 0xbfb8aa3b, v39
	v_exp_f32_e32 v52, v50
	v_add_f32_e32 v47, 1.0, v47
	v_add_f32_e32 v34, 1.0, v34
	v_add_f32_e32 v46, 1.0, v46
	v_rcp_f32_e32 v50, v47
	v_add_f32_e32 v47, 1.0, v51
	v_rcp_f32_e32 v34, v34
	v_rcp_f32_e32 v35, v35
	v_rcp_f32_e32 v37, v37
	v_rcp_f32_e32 v46, v46
	v_rcp_f32_e32 v47, v47
	v_add_f32_e32 v51, 1.0, v52
	v_rcp_f32_e32 v51, v51
	v_pk_mul_f32 v[34:35], v[48:49], v[34:35]
	v_pk_mul_f32 v[36:37], v[44:45], v[36:37]
	v_pk_mul_f32 v[52:53], v[42:43], v[46:47]
	v_pk_mul_f32 v[46:47], v[38:39], v[50:51]
	v_lshl_add_u64 v[50:51], s[62:63], 0, v[40:41]
	v_cvt_pk_bf16_f32 v34, v34, v35
	v_cvt_pk_bf16_f32 v35, v52, v53
	v_cvt_pk_bf16_f32 v36, v36, v37
	s_mov_b64 s[4:5], 0

; __device__ __forceinline__ float fast_exp(float x) { return __builtin_amdgcn_exp2f(x * LOG2E); }
; __device__ __forceinline__ float silu_f(float x) { return x * __builtin_amdgcn_rcpf(1.f + fast_exp(-x)); }
; __device__ __forceinline__ void st_bf8(bf16* p, const f32x4 a, const f32x4 b) { *(GAS v4u*)p = (v4u){pk2(a.x, a.y), pk2(a.z, a.w), pk2(b.x, b.y), pk2(b.z, b.w)}; }
; __device__ __forceinline__ size_t tile_ub(int rowb, int colb, int K) {
;     return ((size_t)(rowb >> 8) * (K >> 6) + (colb >> 6)) * 32768 + (size_t)((rowb >> 7) & 1) * 16384 + (size_t)((((rowb & 127) >> 4) * 2 + ((colb >> 5) & 1)) * 1024);
; }
;     template <int NR> __device__ __forceinline__ void rows(const int (&rowb)[NR], int fr, const float (&rstd)[NR], const f32x4 (&a)[NR][2][2], int pn, int wc, int fq) const {
;     ...
;         for (int i = 0; i < NR; ++i) {
;             const float rr = rstd[i];
; #pragma unroll
;             for (int bj = 0; bj < 2; ++bj) {
;                 f32x4 u = a[i][bj][0] * rr, v = a[i][bj][1] * rr;
;                 const size_t off = (tile_ub(rowb[i], c0b + 32 * bj, DM) + ltb) >> 1;
;                 if (blk == 0) {
; #pragma unroll
;                     for (int j = 0; j < 4; ++j) { u[j] = silu_f(u[j]); v[j] = silu_f(v[j]); }
;                     st_bf8(QH + off, u, v);
;                 } else if (blk == 1) {
; #pragma unroll
;                     for (int j = 0; j < 4; ++j) { const float s0 = __builtin_amdgcn_rcpf(1.f + fast_exp(-u[j])), s1 = __builtin_amdgcn_rcpf(1.f + fast_exp(-v[j])); u[j] = __logf(l[bj][0][j] + (1.f - l[bj][0][j]) * s0); v[j] = __logf(l[bj][1][j] + (1.f - l[bj][1][j]) * s1); }
;                     st_bf8(LOGF + off, u, v);
;                 } else if (blk == 2) {
;                     st_bf8(VH + off, u, v);
;                 } else {
; #pragma unroll
;                     for (int j = 0; j < 4; ++j) { u[j] = silu_f(u[j]); v[j] = silu_f(v[j]); }
;                     st_bf8(GH + off, u, v);
;                 }
.LBB0_424:
	s_add_i32 s4, s6, 0xa0
	s_ashr_i32 s0, s4, 8
	s_ashr_i32 s1, s0, 31
	s_lshl_b64 s[84:85], s[0:1], 19
	s_lshl_b32 s0, s4, 7
	v_cvt_pk_bf16_f32 v37, v46, v47
	s_and_b32 s1, s0, 0x4000
	s_and_b32 s0, s0, 0x3000
	global_store_dwordx4 v[50:51], v[34:37], off sc1
	s_or_b32 s1, s84, s1
	s_waitcnt lgkmcnt(0)
	v_pk_mul_f32 v[38:39], v[30:31], v[82:83] op_sel_hi:[1,0]
	v_pk_mul_f32 v[36:37], v[26:27], v[82:83] op_sel_hi:[1,0]
	v_or_b32_e32 v26, s0, v170
	v_pk_mul_f32 v[34:35], v[32:33], v[82:83] op_sel_hi:[1,0]
	v_pk_mul_f32 v[32:33], v[28:29], v[82:83] op_sel_hi:[1,0]
	v_or_b32_e32 v30, s1, v26
	v_mov_b32_e32 v31, s85
	s_and_b64 vcc, exec, s[12:13]
	s_mov_b64 s[4:5], -1
	s_cbranch_vccnz .LBB0_434
	s_and_b64 vcc, exec, s[10:11]
	s_cbranch_vccnz .LBB0_431
	s_andn2_b64 vcc, exec, s[82:83]
	s_cbranch_vccnz .LBB0_428
	v_mul_f32_e32 v27, 0xbfb8aa3b, v36
	v_mul_f32_e32 v28, 0xbfb8aa3b, v39
	v_exp_f32_e32 v27, v27
	v_exp_f32_e32 v29, v28
	v_mul_f32_e32 v28, 0xbfb8aa3b, v37
	v_exp_f32_e32 v40, v28
	v_add_f32_e32 v27, 1.0, v27
	v_mul_f32_e32 v41, 0xbfb8aa3b, v32
	v_mul_f32_e32 v26, 0xbfb8aa3b, v38
	v_rcp_f32_e32 v28, v27
	v_add_f32_e32 v27, 1.0, v29
	v_add_f32_e32 v29, 1.0, v40
	v_mul_f32_e32 v40, 0xbfb8aa3b, v34
	v_exp_f32_e32 v41, v41
	v_mul_f32_e32 v42, 0xbfb8aa3b, v35
	v_exp_f32_e32 v26, v26
	v_exp_f32_e32 v40, v40
	v_exp_f32_e32 v43, v42
	v_mul_f32_e32 v42, 0xbfb8aa3b, v33
	v_exp_f32_e32 v44, v42
	v_add_f32_e32 v41, 1.0, v41
	v_add_f32_e32 v26, 1.0, v26
	v_add_f32_e32 v40, 1.0, v40
	v_rcp_f32_e32 v42, v41
	v_add_f32_e32 v41, 1.0, v43
	v_rcp_f32_e32 v26, v26
	v_rcp_f32_e32 v27, v27
	v_rcp_f32_e32 v29, v29
	v_rcp_f32_e32 v40, v40
	v_rcp_f32_e32 v41, v41
	v_add_f32_e32 v43, 1.0, v44
	v_rcp_f32_e32 v43, v43
	v_pk_mul_f32 v[26:27], v[38:39], v[26:27]
	v_pk_mul_f32 v[28:29], v[36:37], v[28:29]
	v_pk_mul_f32 v[44:45], v[34:35], v[40:41]
	v_pk_mul_f32 v[40:41], v[32:33], v[42:43]
	v_lshl_add_u64 v[42:43], s[62:63], 0, v[30:31]
	v_cvt_pk_bf16_f32 v26, v26, v27
	v_cvt_pk_bf16_f32 v27, v44, v45
	v_cvt_pk_bf16_f32 v28, v28, v29
	s_mov_b64 s[4:5], 0

; __device__ __forceinline__ float fast_exp(float x) { return __builtin_amdgcn_exp2f(x * LOG2E); }
; __device__ __forceinline__ float silu_f(float x) { return x * __builtin_amdgcn_rcpf(1.f + fast_exp(-x)); }
; __device__ __forceinline__ void st_bf8(bf16* p, const f32x4 a, const f32x4 b) { *(GAS v4u*)p = (v4u){pk2(a.x, a.y), pk2(a.z, a.w), pk2(b.x, b.y), pk2(b.z, b.w)}; }
;     template <int NR> __device__ __forceinline__ void rows(const int (&rowb)[NR], int fr, const float (&rstd)[NR], const f32x4 (&a)[NR][2][2], int pn, int wc, int fq) const {
;     ...
;         for (int i = 0; i < NR; ++i) {
;             const float rr = rstd[i];
; #pragma unroll
;             for (int bj = 0; bj < 2; ++bj) {
;                 f32x4 u = a[i][bj][0] * rr, v = a[i][bj][1] * rr;
;                 const size_t off = (tile_ub(rowb[i], c0b + 32 * bj, DM) + ltb) >> 1;
;                 if (blk == 0) {
; #pragma unroll
;                     for (int j = 0; j < 4; ++j) { u[j] = silu_f(u[j]); v[j] = silu_f(v[j]); }
;                     st_bf8(QH + off, u, v);
;                 } else if (blk == 1) {
; #pragma unroll
;                     for (int j = 0; j < 4; ++j) { const float s0 = __builtin_amdgcn_rcpf(1.f + fast_exp(-u[j])), s1 = __builtin_amdgcn_rcpf(1.f + fast_exp(-v[j])); u[j] = __logf(l[bj][0][j] + (1.f - l[bj][0][j]) * s0); v[j] = __logf(l[bj][1][j] + (1.f - l[bj][1][j]) * s1); }
;                     st_bf8(LOGF + off, u, v);
;                 } else if (blk == 2) {
;                     st_bf8(VH + off, u, v);
;                 } else {
; #pragma unroll
;                     for (int j = 0; j < 4; ++j) { u[j] = silu_f(u[j]); v[j] = silu_f(v[j]); }
;                     st_bf8(GH + off, u, v);
;                 }
.LBB0_436:
	s_nop 0
	v_cvt_pk_bf16_f32 v29, v40, v41
	v_mov_b32_e32 v34, v82
	v_mov_b32_e32 v35, v82
	global_store_dwordx4 v[42:43], v[26:29], off sc1
	v_pk_mul_f32 v[32:33], v[22:23], v[34:35]
	s_and_b64 vcc, exec, s[12:13]
	v_mov_b32_e32 v28, v82
	v_mov_b32_e32 v29, v82
	v_pk_mul_f32 v[26:27], v[24:25], v[28:29]
	v_pk_mul_f32 v[22:23], v[20:21], v[28:29]
	v_pk_mul_f32 v[28:29], v[18:19], v[34:35]
	v_or_b32_e32 v24, 0x400, v30
	v_mov_b32_e32 v25, s85
	s_mov_b64 s[4:5], -1
	s_cbranch_vccnz .LBB0_446
	s_and_b64 vcc, exec, s[10:11]
	s_cbranch_vccnz .LBB0_443
	s_andn2_b64 vcc, exec, s[82:83]
	s_cbranch_vccnz .LBB0_440
	v_mul_f32_e32 v19, 0xbfb8aa3b, v28
	v_mul_f32_e32 v20, 0xbfb8aa3b, v33
	v_exp_f32_e32 v19, v19
	v_exp_f32_e32 v21, v20
	v_mul_f32_e32 v20, 0xbfb8aa3b, v29
	v_exp_f32_e32 v30, v20
	v_add_f32_e32 v19, 1.0, v19
	v_mul_f32_e32 v31, 0xbfb8aa3b, v22
	v_mul_f32_e32 v18, 0xbfb8aa3b, v32
	v_rcp_f32_e32 v20, v19
	v_add_f32_e32 v19, 1.0, v21
	v_add_f32_e32 v21, 1.0, v30
	v_mul_f32_e32 v30, 0xbfb8aa3b, v26
	v_exp_f32_e32 v31, v31
	v_mul_f32_e32 v34, 0xbfb8aa3b, v27
	v_exp_f32_e32 v18, v18
	v_exp_f32_e32 v30, v30
	v_exp_f32_e32 v35, v34
	v_mul_f32_e32 v34, 0xbfb8aa3b, v23
	v_exp_f32_e32 v36, v34
	v_add_f32_e32 v31, 1.0, v31
	v_add_f32_e32 v18, 1.0, v18
	v_add_f32_e32 v30, 1.0, v30
	v_rcp_f32_e32 v34, v31
	v_add_f32_e32 v31, 1.0, v35
	v_rcp_f32_e32 v18, v18
	v_rcp_f32_e32 v19, v19
	v_rcp_f32_e32 v21, v21
	v_rcp_f32_e32 v30, v30
	v_rcp_f32_e32 v31, v31
	v_add_f32_e32 v35, 1.0, v36
	v_rcp_f32_e32 v35, v35
	v_pk_mul_f32 v[18:19], v[32:33], v[18:19]
	v_pk_mul_f32 v[20:21], v[28:29], v[20:21]
	v_pk_mul_f32 v[36:37], v[26:27], v[30:31]
	v_pk_mul_f32 v[30:31], v[22:23], v[34:35]
	v_lshl_add_u64 v[34:35], s[62:63], 0, v[24:25]
	v_cvt_pk_bf16_f32 v18, v18, v19
	v_cvt_pk_bf16_f32 v19, v36, v37
	v_cvt_pk_bf16_f32 v20, v20, v21
	s_mov_b64 s[4:5], 0

; __device__ __forceinline__ float fast_exp(float x) { return __builtin_amdgcn_exp2f(x * LOG2E); }
; __device__ __forceinline__ float silu_f(float x) { return x * __builtin_amdgcn_rcpf(1.f + fast_exp(-x)); }
; __device__ __forceinline__ void st_bf8(bf16* p, const f32x4 a, const f32x4 b) { *(GAS v4u*)p = (v4u){pk2(a.x, a.y), pk2(a.z, a.w), pk2(b.x, b.y), pk2(b.z, b.w)}; }
; __device__ __forceinline__ size_t tile_ub(int rowb, int colb, int K) {
;     return ((size_t)(rowb >> 8) * (K >> 6) + (colb >> 6)) * 32768 + (size_t)((rowb >> 7) & 1) * 16384 + (size_t)((((rowb & 127) >> 4) * 2 + ((colb >> 5) & 1)) * 1024);
; }
;     template <int NR> __device__ __forceinline__ void rows(const int (&rowb)[NR], int fr, const float (&rstd)[NR], const f32x4 (&a)[NR][2][2], int pn, int wc, int fq) const {
;     ...
;         for (int i = 0; i < NR; ++i) {
;             const float rr = rstd[i];
; #pragma unroll
;             for (int bj = 0; bj < 2; ++bj) {
;                 f32x4 u = a[i][bj][0] * rr, v = a[i][bj][1] * rr;
;                 const size_t off = (tile_ub(rowb[i], c0b + 32 * bj, DM) + ltb) >> 1;
;                 if (blk == 0) {
; #pragma unroll
;                     for (int j = 0; j < 4; ++j) { u[j] = silu_f(u[j]); v[j] = silu_f(v[j]); }
;                     st_bf8(QH + off, u, v);
;                 } else if (blk == 1) {
; #pragma unroll
;                     for (int j = 0; j < 4; ++j) { const float s0 = __builtin_amdgcn_rcpf(1.f + fast_exp(-u[j])), s1 = __builtin_amdgcn_rcpf(1.f + fast_exp(-v[j])); u[j] = __logf(l[bj][0][j] + (1.f - l[bj][0][j]) * s0); v[j] = __logf(l[bj][1][j] + (1.f - l[bj][1][j]) * s1); }
;                     st_bf8(LOGF + off, u, v);
;                 } else if (blk == 2) {
;                     st_bf8(VH + off, u, v);
;                 } else {
; #pragma unroll
;                     for (int j = 0; j < 4; ++j) { u[j] = silu_f(u[j]); v[j] = silu_f(v[j]); }
;                     st_bf8(GH + off, u, v);
;                 }
.LBB0_448:
	s_addk_i32 s6, 0xb0
	s_ashr_i32 s0, s6, 8
	s_ashr_i32 s1, s0, 31
	v_cvt_pk_bf16_f32 v21, v30, v31
	s_lshl_b64 s[84:85], s[0:1], 19
	s_lshl_b32 s0, s6, 7
	global_store_dwordx4 v[34:35], v[18:21], off sc1
	s_and_b32 s1, s0, 0x4000
	s_and_b32 s0, s0, 0x3800
	v_mov_b32_e32 v20, v83
	v_pk_mul_f32 v[18:19], v[16:17], v[20:21] op_sel_hi:[1,0]
	v_pk_mul_f32 v[22:23], v[14:15], v[20:21] op_sel_hi:[1,0]
	v_pk_mul_f32 v[16:17], v[12:13], v[20:21] op_sel_hi:[1,0]
	v_pk_mul_f32 v[20:21], v[10:11], v[20:21] op_sel_hi:[1,0]
	s_or_b32 s1, s84, s1
	v_or_b32_e32 v10, s0, v170
	v_or_b32_e32 v14, s1, v10
	v_mov_b32_e32 v15, s85
	s_and_b64 vcc, exec, s[12:13]
	s_mov_b64 s[4:5], -1
	s_cbranch_vccnz .LBB0_458
	s_and_b64 vcc, exec, s[10:11]
	s_cbranch_vccnz .LBB0_455
	s_andn2_b64 vcc, exec, s[82:83]
	s_cbranch_vccnz .LBB0_452
	v_mul_f32_e32 v11, 0xbfb8aa3b, v20
	v_mul_f32_e32 v12, 0xbfb8aa3b, v23
	v_exp_f32_e32 v11, v11
	v_exp_f32_e32 v13, v12
	v_mul_f32_e32 v12, 0xbfb8aa3b, v21
	v_exp_f32_e32 v24, v12
	v_add_f32_e32 v11, 1.0, v11
	v_mul_f32_e32 v25, 0xbfb8aa3b, v16
	v_mul_f32_e32 v10, 0xbfb8aa3b, v22
	v_rcp_f32_e32 v12, v11
	v_add_f32_e32 v11, 1.0, v13
	v_add_f32_e32 v13, 1.0, v24
	v_mul_f32_e32 v24, 0xbfb8aa3b, v18
	v_exp_f32_e32 v25, v25
	v_mul_f32_e32 v26, 0xbfb8aa3b, v19
	v_exp_f32_e32 v10, v10
	v_exp_f32_e32 v24, v24
	v_exp_f32_e32 v27, v26
	v_mul_f32_e32 v26, 0xbfb8aa3b, v17
	v_exp_f32_e32 v28, v26
	v_add_f32_e32 v25, 1.0, v25
	v_add_f32_e32 v10, 1.0, v10
	v_add_f32_e32 v24, 1.0, v24
	v_rcp_f32_e32 v26, v25
	v_add_f32_e32 v25, 1.0, v27
	v_rcp_f32_e32 v10, v10
	v_rcp_f32_e32 v11, v11
	v_rcp_f32_e32 v13, v13
	v_rcp_f32_e32 v24, v24
	v_rcp_f32_e32 v25, v25
	v_add_f32_e32 v27, 1.0, v28
	v_rcp_f32_e32 v27, v27
	v_pk_mul_f32 v[10:11], v[22:23], v[10:11]
	v_pk_mul_f32 v[12:13], v[20:21], v[12:13]
	v_pk_mul_f32 v[28:29], v[18:19], v[24:25]
	v_pk_mul_f32 v[24:25], v[16:17], v[26:27]
	v_lshl_add_u64 v[26:27], s[62:63], 0, v[14:15]
	v_cvt_pk_bf16_f32 v10, v10, v11
	v_cvt_pk_bf16_f32 v11, v28, v29
	v_cvt_pk_bf16_f32 v12, v12, v13
	s_mov_b64 s[4:5], 0

; __device__ __forceinline__ float fast_exp(float x) { return __builtin_amdgcn_exp2f(x * LOG2E); }
; __device__ __forceinline__ float silu_f(float x) { return x * __builtin_amdgcn_rcpf(1.f + fast_exp(-x)); }
; __device__ __forceinline__ void st_bf8(bf16* p, const f32x4 a, const f32x4 b) { *(GAS v4u*)p = (v4u){pk2(a.x, a.y), pk2(a.z, a.w), pk2(b.x, b.y), pk2(b.z, b.w)}; }
;     template <int NR> __device__ __forceinline__ void rows(const int (&rowb)[NR], int fr, const float (&rstd)[NR], const f32x4 (&a)[NR][2][2], int pn, int wc, int fq) const {
;     ...
;         for (int i = 0; i < NR; ++i) {
;             const float rr = rstd[i];
; #pragma unroll
;             for (int bj = 0; bj < 2; ++bj) {
;                 f32x4 u = a[i][bj][0] * rr, v = a[i][bj][1] * rr;
;                 const size_t off = (tile_ub(rowb[i], c0b + 32 * bj, DM) + ltb) >> 1;
;                 if (blk == 0) {
; #pragma unroll
;                     for (int j = 0; j < 4; ++j) { u[j] = silu_f(u[j]); v[j] = silu_f(v[j]); }
;                     st_bf8(QH + off, u, v);
;                 } else if (blk == 1) {
; #pragma unroll
;                     for (int j = 0; j < 4; ++j) { const float s0 = __builtin_amdgcn_rcpf(1.f + fast_exp(-u[j])), s1 = __builtin_amdgcn_rcpf(1.f + fast_exp(-v[j])); u[j] = __logf(l[bj][0][j] + (1.f - l[bj][0][j]) * s0); v[j] = __logf(l[bj][1][j] + (1.f - l[bj][1][j]) * s1); }
;                     st_bf8(LOGF + off, u, v);
;                 } else if (blk == 2) {
;                     st_bf8(VH + off, u, v);
;                 } else {
; #pragma unroll
;                     for (int j = 0; j < 4; ++j) { u[j] = silu_f(u[j]); v[j] = silu_f(v[j]); }
;                     st_bf8(GH + off, u, v);
;                 }
.LBB0_460:
	s_nop 0
	v_cvt_pk_bf16_f32 v13, v24, v25
	v_mov_b32_e32 v82, v83
	global_store_dwordx4 v[26:27], v[10:13], off sc1
	v_pk_mul_f32 v[16:17], v[6:7], v[82:83]
	s_and_b64 vcc, exec, s[12:13]
	v_mov_b32_e32 v12, v83
	v_mov_b32_e32 v13, v83
	v_pk_mul_f32 v[10:11], v[8:9], v[12:13]
	v_pk_mul_f32 v[6:7], v[4:5], v[12:13]
	v_pk_mul_f32 v[12:13], v[2:3], v[82:83]
	v_or_b32_e32 v8, 0x400, v14
	v_mov_b32_e32 v9, s85
	s_mov_b64 s[4:5], -1
	s_cbranch_vccnz .LBB0_470
	s_and_b64 vcc, exec, s[10:11]
	s_cbranch_vccnz .LBB0_467
	s_andn2_b64 vcc, exec, s[82:83]
	s_cbranch_vccnz .LBB0_464
	v_mul_f32_e32 v3, 0xbfb8aa3b, v12
	v_mul_f32_e32 v4, 0xbfb8aa3b, v17
	v_exp_f32_e32 v3, v3
	v_exp_f32_e32 v5, v4
	v_mul_f32_e32 v4, 0xbfb8aa3b, v13
	v_exp_f32_e32 v14, v4
	v_add_f32_e32 v3, 1.0, v3
	v_mul_f32_e32 v15, 0xbfb8aa3b, v6
	v_mul_f32_e32 v2, 0xbfb8aa3b, v16
	v_rcp_f32_e32 v4, v3
	v_add_f32_e32 v3, 1.0, v5
	v_add_f32_e32 v5, 1.0, v14
	v_mul_f32_e32 v14, 0xbfb8aa3b, v10
	v_exp_f32_e32 v15, v15
	v_mul_f32_e32 v18, 0xbfb8aa3b, v11
	v_exp_f32_e32 v2, v2
	v_exp_f32_e32 v14, v14
	v_exp_f32_e32 v19, v18
	v_mul_f32_e32 v18, 0xbfb8aa3b, v7
	v_exp_f32_e32 v20, v18
	v_add_f32_e32 v15, 1.0, v15
	v_add_f32_e32 v2, 1.0, v2
	v_add_f32_e32 v14, 1.0, v14
	v_rcp_f32_e32 v18, v15
	v_add_f32_e32 v15, 1.0, v19
	v_rcp_f32_e32 v2, v2
	v_rcp_f32_e32 v3, v3
	v_rcp_f32_e32 v5, v5
	v_rcp_f32_e32 v14, v14
	v_rcp_f32_e32 v15, v15
	v_add_f32_e32 v19, 1.0, v20
	v_rcp_f32_e32 v19, v19
	v_pk_mul_f32 v[2:3], v[16:17], v[2:3]
	v_pk_mul_f32 v[4:5], v[12:13], v[4:5]
	v_pk_mul_f32 v[20:21], v[10:11], v[14:15]
	v_pk_mul_f32 v[14:15], v[6:7], v[18:19]
	v_lshl_add_u64 v[18:19], s[62:63], 0, v[8:9]
	v_cvt_pk_bf16_f32 v2, v2, v3
	v_cvt_pk_bf16_f32 v3, v20, v21
	v_cvt_pk_bf16_f32 v4, v4, v5
	s_mov_b64 s[4:5], 0

; #define PG8_BAR __builtin_amdgcn_s_barrier()
; __device__ __forceinline__ void st_bf8(bf16* p, const f32x4 a, const f32x4 b) { *(GAS v4u*)p = (v4u){pk2(a.x, a.y), pk2(a.z, a.w), pk2(b.x, b.y), pk2(b.z, b.w)}; }
; template <class Epi, class Sched>
; __device__ __forceinline__ void gemm_phase(PG8_LAS unsigned char* lds, const Gemm g, const Sched& S, const Epi& E) {
;     ...
;         if (!has_next) break;
; #pragma unroll
;         for (int a = 0; a < 2; ++a)
; #pragma unroll
;             for (int b = 0; b < 2; ++b)
; #pragma unroll
;                 for (int m = 0; m < 4; ++m)
; #pragma unroll
;                     for (int n = 0; n < 2; ++n) acc[a][b][m][n] = (f32x4){0.f, 0.f, 0.f, 0.f};
;         cur = nxt; cA = nA; cB = nB; ++ui;
;         if (wr == 1) PG8_BAR;
;     template <int NR> __device__ __forceinline__ void rows(const int (&rowb)[NR], int fr, const float (&rstd)[NR], const f32x4 (&a)[NR][2][2], int pn, int wc, int fq) const {
;     ...
;                     st_bf8(GH + off, u, v);
.LBB0_472:
	s_nop 0
	v_cvt_pk_bf16_f32 v5, v14, v15
	s_andn2_b64 vcc, exec, s[76:77]
	s_mov_b64 s[4:5], -1
	global_store_dwordx4 v[18:19], v[2:5], off sc1
	s_cbranch_vccnz .LBB0_259
	s_andn2_b64 vcc, exec, s[68:69]
	s_cbranch_vccnz .LBB0_258
	s_barrier
	s_branch .LBB0_258

; __device__ __forceinline__ float fast_exp(float x) { return __builtin_amdgcn_exp2f(x * LOG2E); }
;     template <int NR> __device__ __forceinline__ void rows(const int (&rowb)[NR], int fr, const float (&rstd)[NR], const f32x4 (&a)[NR][2][2], int pn, int wc, int fq) const {
;     ...
;         for (int i = 0; i < NR; ++i) {
;             const float rr = rstd[i];
; #pragma unroll
;             for (int bj = 0; bj < 2; ++bj) {
;                 f32x4 u = a[i][bj][0] * rr, v = a[i][bj][1] * rr;
;                 const size_t off = (tile_ub(rowb[i], c0b + 32 * bj, DM) + ltb) >> 1;
;                 if (blk == 0) {
; #pragma unroll
;                     for (int j = 0; j < 4; ++j) { u[j] = silu_f(u[j]); v[j] = silu_f(v[j]); }
;                     st_bf8(QH + off, u, v);
;                 } else if (blk == 1) {
; #pragma unroll
;                     for (int j = 0; j < 4; ++j) { const float s0 = __builtin_amdgcn_rcpf(1.f + fast_exp(-u[j])), s1 = __builtin_amdgcn_rcpf(1.f + fast_exp(-v[j])); u[j] = __logf(l[bj][0][j] + (1.f - l[bj][0][j]) * s0); v[j] = __logf(l[bj][1][j] + (1.f - l[bj][1][j]) * s1); }
;                     st_bf8(LOGF + off, u, v);
;                 } else if (blk == 2) {
;                     st_bf8(VH + off, u, v);
;                 } else {
; #pragma unroll
;                     for (int j = 0; j < 4; ++j) { u[j] = silu_f(u[j]); v[j] = silu_f(v[j]); }
;                     st_bf8(GH + off, u, v);
;                 }
; template <class RowEpi, int MTL>
; __device__ __forceinline__ void small_gemm_t(Frame& F, const bf16* A  , const bf16* Bt, int N, int K, const RowEpi& R, int i_lo, int i_hi) {
;     ...
;         if (w < MTL) {
;             f32x4 s[2][2];
; #pragma unroll
;             for (int bj = 0; bj < 2; ++bj)
; #pragma unroll
;                 for (int n = 0; n < 2; ++n) { f32x4 t = (f32x4){0.f, 0.f, 0.f, 0.f};
; #pragma unroll
;                     for (int ww = 0; ww < 8; ++ww) t += part[(ww * (4 * MTL) + w * 4 + bj * 2 + n) * 64 + lane];
;                     s[bj][n] = t; }
;             const int row1[1] = {MP + rb * 16 * MTL + 16 * w}; const f32x4 a1[1][2][2] = {{{s[0][0], s[0][1]}, {s[1][0], s[1][1]}}};
;             const float rr1[1] = {rsp ? rsqrtf(rsv * (1.f / DM) + EPS) : 1.f};
;             R.template rows<1>(row1, fr, rr1, a1, pn, wc, fq);
.LBB0_503:
	s_waitcnt lgkmcnt(11)
	v_pk_add_f32 v[72:73], v[72:73], 0 op_sel_hi:[1,0]
	v_pk_add_f32 v[70:71], v[70:71], 0 op_sel_hi:[1,0]
	s_waitcnt lgkmcnt(10)
	v_pk_add_f32 v[40:41], v[40:41], 0 op_sel_hi:[1,0]
	v_pk_add_f32 v[38:39], v[38:39], 0 op_sel_hi:[1,0]
	s_waitcnt lgkmcnt(9)
	v_pk_add_f32 v[68:69], v[72:73], v[68:69]
	v_pk_add_f32 v[66:67], v[70:71], v[66:67]
	s_waitcnt lgkmcnt(8)
	v_pk_add_f32 v[36:37], v[40:41], v[36:37]
	v_pk_add_f32 v[34:35], v[38:39], v[34:35]
	s_waitcnt lgkmcnt(7)
	v_pk_add_f32 v[64:65], v[68:69], v[64:65]
	v_pk_add_f32 v[62:63], v[66:67], v[62:63]
	s_waitcnt lgkmcnt(6)
	v_pk_add_f32 v[32:33], v[36:37], v[32:33]
	v_pk_add_f32 v[30:31], v[34:35], v[30:31]
	s_waitcnt lgkmcnt(5)
	v_pk_add_f32 v[60:61], v[64:65], v[60:61]
	v_pk_add_f32 v[58:59], v[62:63], v[58:59]
	s_waitcnt lgkmcnt(4)
	v_pk_add_f32 v[24:25], v[32:33], v[24:25]
	v_pk_add_f32 v[22:23], v[30:31], v[22:23]
	v_pk_add_f32 v[56:57], v[60:61], v[56:57]
	v_pk_add_f32 v[54:55], v[58:59], v[54:55]
	s_waitcnt lgkmcnt(3)
	v_pk_add_f32 v[24:25], v[24:25], v[28:29]
	v_pk_add_f32 v[22:23], v[22:23], v[26:27]
	v_pk_add_f32 v[48:49], v[56:57], v[48:49]
	v_pk_add_f32 v[46:47], v[54:55], v[46:47]
	s_waitcnt lgkmcnt(2)
	v_pk_add_f32 v[16:17], v[24:25], v[16:17]
	v_pk_add_f32 v[14:15], v[22:23], v[14:15]
	v_pk_add_f32 v[48:49], v[48:49], v[52:53]
	v_pk_add_f32 v[46:47], v[46:47], v[50:51]
	s_waitcnt lgkmcnt(1)
	v_pk_add_f32 v[16:17], v[16:17], v[20:21]
	v_pk_add_f32 v[14:15], v[14:15], v[18:19]
	v_mov_b32_e32 v87, v86
	v_pk_add_f32 v[44:45], v[48:49], v[44:45]
	v_pk_add_f32 v[42:43], v[46:47], v[42:43]
	s_waitcnt lgkmcnt(0)
	v_pk_add_f32 v[12:13], v[16:17], v[12:13]
	v_pk_add_f32 v[10:11], v[14:15], v[10:11]
	v_mov_b32_e32 v14, v86
	v_mov_b32_e32 v15, v86
	s_bitset1_b32 s12, 10
	v_cvt_pk_bf16_f32 v85, v100, v101
	v_pk_mul_f32 v[16:17], v[14:15], v[44:45]
	v_pk_mul_f32 v[18:19], v[86:87], v[42:43]
	v_pk_mul_f32 v[14:15], v[14:15], v[12:13]
	v_pk_mul_f32 v[22:23], v[86:87], v[10:11]
	v_lshl_add_u64 v[20:21], v[88:89], 0, s[12:13]
	s_andn2_b64 vcc, exec, s[24:25]
	s_mov_b64 s[8:9], -1
	global_store_dwordx4 v[102:103], v[82:85], off sc1
	s_cbranch_vccnz .LBB0_513
	s_andn2_b64 vcc, exec, s[22:23]
	s_cbranch_vccnz .LBB0_510
	s_andn2_b64 vcc, exec, s[4:5]
	s_mov_b64 s[4:5], -1
	s_cbranch_vccnz .LBB0_507
	v_mul_f32_e32 v11, 0xbfb8aa3b, v22
	v_mul_f32_e32 v12, 0xbfb8aa3b, v19
	v_exp_f32_e32 v11, v11
	v_exp_f32_e32 v13, v12
	v_mul_f32_e32 v12, 0xbfb8aa3b, v23
	v_exp_f32_e32 v24, v12
	v_add_f32_e32 v11, 1.0, v11
	v_mul_f32_e32 v25, 0xbfb8aa3b, v14
	v_mul_f32_e32 v10, 0xbfb8aa3b, v18
	v_rcp_f32_e32 v12, v11
	v_add_f32_e32 v11, 1.0, v13
	v_add_f32_e32 v13, 1.0, v24
	v_mul_f32_e32 v24, 0xbfb8aa3b, v16
	v_exp_f32_e32 v25, v25
	v_mul_f32_e32 v26, 0xbfb8aa3b, v17
	v_exp_f32_e32 v10, v10
	v_exp_f32_e32 v24, v24
	v_exp_f32_e32 v27, v26
	v_mul_f32_e32 v26, 0xbfb8aa3b, v15
	v_exp_f32_e32 v28, v26
	v_add_f32_e32 v25, 1.0, v25
	v_add_f32_e32 v10, 1.0, v10
	v_add_f32_e32 v24, 1.0, v24
	v_rcp_f32_e32 v26, v25
	v_add_f32_e32 v25, 1.0, v27
	v_rcp_f32_e32 v10, v10
	v_rcp_f32_e32 v11, v11
	v_rcp_f32_e32 v13, v13
	v_rcp_f32_e32 v24, v24
	v_rcp_f32_e32 v25, v25
	v_add_f32_e32 v27, 1.0, v28
	v_rcp_f32_e32 v27, v27
	v_pk_mul_f32 v[10:11], v[18:19], v[10:11]
	v_pk_mul_f32 v[12:13], v[22:23], v[12:13]
	v_pk_mul_f32 v[28:29], v[16:17], v[24:25]
	v_pk_mul_f32 v[24:25], v[14:15], v[26:27]
	v_lshl_add_u64 v[26:27], s[62:63], 0, v[20:21]
	v_cvt_pk_bf16_f32 v10, v10, v11
	v_cvt_pk_bf16_f32 v11, v28, v29
	v_cvt_pk_bf16_f32 v12, v12, v13
	s_mov_b64 s[4:5], 0
